# v78 + K-loops: A-fragment ds_read base constants folded into the offset field over one persistent base register (4 v_add_u32 per 2 K-tiles removed)
# speedup vs baseline: 1.0032x; 1.0032x over previous
; __device__ __forceinline__ int opaque_tid() { int t = (int)threadIdx.x; asm volatile("" : "+v"(t)); return t; }
; #define PG8_STAGE(bufoff, gbase, voff) do { _Pragma("unroll") for (int _i = 0; _i < 2; ++_i) \
;         __builtin_amdgcn_global_load_lds((const unsigned*)((const char*)(gbase) + (voff)[_i]), (PG8_LAS unsigned*)(lds + (bufoff) + ldsw + _i * 8192), 16, 0, 0); } while (0)
; #define PG8_WAIT_V(n) asm volatile("s_waitcnt vmcnt(" #n ")" ::: "memory")
; #define PG8_BAR __builtin_amdgcn_s_barrier()
; template <class Epi, class Sched, bool ALIGN_EPI = false, bool SP2 = false>
; __device__ __forceinline__ void gemm_phase(PG8_LAS unsigned char* lds, const Gemm g, const Sched& S, const Epi& E) {
;     const int tid = opaque_tid(), wid = __builtin_amdgcn_readfirstlane(tid >> 6), lane = tid & 63, wr = wid >> 2, wc = wid & 3, fr = lane & 15, fq = lane >> 4;
;     const int K = g.K, nt = K / BK;
;     unsigned voffA[2], voffB[2];
; #pragma unroll
;     for (int i = 0; i < 2; ++i) { int R, C; stage_rc(tid * 16 + i * 8192, R, C); const int Rb = Epi::PERM ? ((R & ~31) + perm32(R & 31)) : R;
;         voffA[i] = (unsigned)(R * K + C) * 2u; voffB[i] = (unsigned)(Rb * K + C) * 2u; }
;     const size_t kstep = (size_t)(BK * 2);
;     const size_t hstep = (size_t)HALF * K * 2;
;     const size_t tstep = 2 * hstep;
;     const unsigned ldsw = (unsigned)wid * 1024u;
;     const int aoff = lds_byte(wr * 64 + fr, fq * 8), boff = lds_byte(wc * 32 + fr, fq * 8);
;     ...
;     if constexpr (SP2) {
;         PG8_STAGE(PG8_SB(0, 0), cB, voffB); PG8_STAGE(PG8_SB(0, 1), cB + hstep, voffB); PG8_STAGE(PG8_SA(0, 0), cA, voffA); PG8_STAGE(PG8_SA(0, 1), cA + hstep, voffA);
;         if (wr == 1) PG8_BAR;
;         PG8_WAIT_V(2); PG8_BAR;
;         PG8_STAGE(PG8_SB(1, 0), cB + kstep, voffB); PG8_STAGE(PG8_SA(1, 0), cA + kstep, voffA); PG8_STAGE(PG8_SB(1, 1), cB + hstep + kstep, voffB);
;         PG8_WAIT_V(6); PG8_BAR;
.LBB0_94:
	s_add_u32 s48, s4, 0xa400000
	s_addc_u32 s49, s5, 0
	s_lshl_b32 s7, s78, 7
	s_and_b32 s7, s7, 0x100
	s_add_u32 s22, s16, s7
	s_addc_u32 s23, s17, 0
	s_add_u32 s7, s14, s7
	s_addc_u32 s11, s15, 0
	s_and_b32 s21, s19, 3
	s_add_i32 m0, s42, 0x18000
	v_lshl_add_u64 v[10:11], v[10:11], 0, s[82:83]
	s_lshl_b32 s16, s20, 13
	s_lshl_b32 s17, s21, 12
	s_waitcnt vmcnt(2)
	s_barrier
	global_load_lds_dwordx4 v[10:11], off
	v_lshl_add_u64 v[8:9], v[8:9], 0, s[82:83]
	s_add_i32 m0, s42, 0x1a000
	s_add_i32 s50, s42, 0x8000
	s_add_i32 s51, s42, 0xa000
	global_load_lds_dwordx4 v[8:9], off
	v_lshl_add_u64 v[4:5], v[4:5], 0, s[82:83]
	s_mov_b32 m0, s50
	s_add_u32 s14, s28, 0x40080
	global_load_lds_dwordx4 v[4:5], off
	v_lshl_add_u64 v[4:5], v[6:7], 0, s[82:83]
	s_mov_b32 m0, s51
	s_addc_u32 s15, s29, 0
	global_load_lds_dwordx4 v[4:5], off
	s_add_i32 m0, s42, 0x1c000
	v_lshl_add_u64 v[4:5], s[14:15], 0, v[168:169]
	global_load_lds_dwordx4 v[4:5], off
	v_lshl_add_u64 v[4:5], s[14:15], 0, v[172:173]
	s_add_i32 m0, s42, 0x1e000
	v_bfe_u32 v6, v12, 4, 2
	global_load_lds_dwordx4 v[4:5], off
	v_and_b32_e32 v5, 15, v12
	v_lshlrev_b32_e32 v4, 4, v6
	v_lshlrev_b32_e32 v7, 2, v12
	v_lshl_or_b32 v3, s20, 6, v5
	v_lshl_or_b32 v5, v5, 6, v4
	v_and_b32_e32 v7, 32, v7
	s_cmpk_lt_u32 s18, 0x100
	v_bitop3_b32 v9, v5, s16, v7 bitop3:0xde
	v_bitop3_b32 v204, v5, s17, v7 bitop3:0xde
	v_add_u32_e32 v204, 0x10000, v204
	s_cselect_b64 s[14:15], -1, 0
	s_ashr_i32 s52, s34, 31
	v_mov_b32_e32 v5, v2
	s_cmp_lg_u32 s3, 0
	v_lshl_add_u64 v[4:5], s[4:5], 0, v[4:5]
	s_mov_b64 s[2:3], 0x1a400000
	v_lshl_add_u64 v[176:177], v[4:5], 0, s[2:3]
	v_lshlrev_b32_e32 v5, 14, v13
	v_lshlrev_b32_e32 v8, 3, v6
	v_lshlrev_b32_e32 v6, 5, v6
	v_mov_b32_e32 v7, v2
	v_and_b32_e32 v5, 0xffff8000, v5
	v_lshl_add_u64 v[174:175], s[22:23], 0, v[6:7]
	v_lshl_add_u32 v5, v14, 11, v5
	v_and_b32_e32 v6, 1, v13
	v_lshl_or_b32 v5, v6, 6, v5
	v_lshl_add_u32 v178, v15, 1, v5
	v_lshlrev_b32_e32 v5, 14, v16
	v_and_b32_e32 v5, 0xffff8000, v5
	s_waitcnt vmcnt(6)
	s_cselect_b64 s[16:17], -1, 0
	s_sub_u32 s18, s7, s22
	v_lshl_add_u32 v5, v17, 11, v5
	v_and_b32_e32 v6, 1, v16
	s_subb_u32 s19, s11, s23
	v_lshl_or_b32 v4, s21, 6, v8
	v_lshl_or_b32 v5, v6, 6, v5
	s_mov_b32 s72, 0
	s_ashr_i64 s[18:19], s[18:19], 2
	v_mov_b32_e32 v179, v2
	v_lshl_add_u32 v180, v18, 1, v5
	v_mov_b32_e32 v181, v2
	v_add_u32_e32 v205, 0, v9
	v_lshlrev_b32_e32 v206, 1, v4
	s_barrier
	s_branch .LBB0_97

; #define PG8_STAGE(bufoff, gbase, voff) do { _Pragma("unroll") for (int _i = 0; _i < 2; ++_i) \
;         __builtin_amdgcn_global_load_lds((const unsigned*)((const char*)(gbase) + (voff)[_i]), (PG8_LAS unsigned*)(lds + (bufoff) + ldsw + _i * 8192), 16, 0, 0); } while (0)
; #define PG8_LDA(dst, b, h) do { _Pragma("unroll") for (int m = 0; m < 4; ++m) _Pragma("unroll") for (int k = 0; k < 2; ++k) dst[m][k] = *(const PG8_LAS bf16x8*)(lds + PG8_SA(b, h) + aoff + m * 2048 + k * 1024); } while (0)
; #define PG8_LDB(dst, b, h) do { _Pragma("unroll") for (int n = 0; n < 2; ++n) _Pragma("unroll") for (int k = 0; k < 2; ++k) dst[n][k] = *(const PG8_LAS bf16x8*)(lds + PG8_SB(b, h) + boff + n * 2048 + k * 1024); } while (0)
; #define PG8_MMA(ai, bj, At, Bt) do { __builtin_amdgcn_s_setprio(1); _Pragma("unroll") for (int m = 0; m < 4; ++m) _Pragma("unroll") for (int n = 0; n < 2; ++n) _Pragma("unroll") for (int k = 0; k < 2; ++k) \
;         acc[ai][bj][m][n] = __builtin_amdgcn_mfma_f32_16x16x32_bf16(Bt[n][k], At[m][k], acc[ai][bj][m][n], 0, 0, 0); __builtin_amdgcn_s_setprio(0); } while (0)
; #define PG8_WAIT_V(n) asm volatile("s_waitcnt vmcnt(" #n ")" ::: "memory")
; #define PG8_WAIT_L(n) asm volatile("s_waitcnt lgkmcnt(" #n ")" ::: "memory")
; #define PG8_BAR __builtin_amdgcn_s_barrier()
; #define PG8_SCHED __builtin_amdgcn_sched_barrier(0)
; template <class Epi, class Sched, bool ALIGN_EPI = false, bool SP2 = false>
; __device__ __forceinline__ void gemm_phase(PG8_LAS unsigned char* lds, const Gemm g, const Sched& S, const Epi& E) {
;     ...
;             PG8_LDB(B0, 0, 0); PG8_LDB(B1, 0, 1); PG8_SCHED; PG8_LDA(At, 0, 0); PG8_STAGE(PG8_SA(1, 1), a1 + hstep, voffA);
;             PG8_WAIT_V(8); PG8_WAIT_L(0); PG8_BAR; PG8_MMA(0, 0, At, B0); PG8_MMA(0, 1, At, B1); PG8_BAR; PG8_SCHED;
.LBB0_100:
	s_add_u32 s28, s8, 0xfffc0080
	s_addc_u32 s29, s9, -1
	s_add_i32 s53, 0, 0x10000
	s_cmp_eq_u32 s45, 12
	s_cselect_b32 s31, s3, s29
	s_cselect_b32 s30, s7, s28
	s_cselect_b32 s29, s11, s44
	s_cselect_b32 s28, s21, s23
	s_add_i32 s56, 0, 0x14000
	ds_read_b128 v[132:135], v204
	ds_read_b128 v[136:139], v204 offset:1024
	ds_read_b128 v[140:143], v204 offset:2048
	ds_read_b128 v[144:147], v204 offset:3072
	ds_read_b128 v[148:151], v204 offset:16384
	ds_read_b128 v[152:155], v204 offset:17408
	ds_read_b128 v[156:159], v204 offset:18432
	ds_read_b128 v[160:163], v204 offset:19456
	v_lshl_add_u64 v[194:195], s[8:9], 0, v[178:179]
	s_add_i32 m0, s42, 0xc000
	ds_read_b128 v[164:167], v205
	ds_read_b128 v[182:185], v205 offset:1024
	ds_read_b128 v[186:189], v205 offset:2048
	ds_read_b128 v[190:193], v205 offset:3072
	ds_read_b128 v[208:211], v205 offset:4096
	ds_read_b128 v[212:215], v205 offset:5120
	ds_read_b128 v[216:219], v205 offset:6144
	ds_read_b128 v[220:223], v205 offset:7168
	global_load_lds_dwordx4 v[194:195], off
	s_add_i32 m0, s42, 0xe000
	v_lshl_add_u64 v[194:195], s[8:9], 0, v[180:181]
	global_load_lds_dwordx4 v[194:195], off
	s_waitcnt vmcnt(8) lgkmcnt(0)
	s_barrier
	s_setprio 1
	v_mfma_f32_16x16x32_bf16 v[128:131], v[132:135], v[164:167], v[128:131]
	v_mfma_f32_16x16x32_bf16 v[124:127], v[140:143], v[164:167], v[124:127]
	v_mfma_f32_16x16x32_bf16 v[112:115], v[132:135], v[186:189], v[112:115]
	v_mfma_f32_16x16x32_bf16 v[108:111], v[140:143], v[186:189], v[108:111]
	v_mfma_f32_16x16x32_bf16 v[96:99], v[132:135], v[208:211], v[96:99]
	v_mfma_f32_16x16x32_bf16 v[92:95], v[140:143], v[208:211], v[92:95]
	v_mfma_f32_16x16x32_bf16 v[80:83], v[132:135], v[216:219], v[80:83]
	v_mfma_f32_16x16x32_bf16 v[76:79], v[140:143], v[216:219], v[76:79]
	v_mfma_f32_16x16x32_bf16 v[128:131], v[136:139], v[182:185], v[128:131]
	v_mfma_f32_16x16x32_bf16 v[124:127], v[144:147], v[182:185], v[124:127]
	v_mfma_f32_16x16x32_bf16 v[112:115], v[136:139], v[190:193], v[112:115]
	v_mfma_f32_16x16x32_bf16 v[108:111], v[144:147], v[190:193], v[108:111]
	v_mfma_f32_16x16x32_bf16 v[96:99], v[136:139], v[212:215], v[96:99]
	v_mfma_f32_16x16x32_bf16 v[92:95], v[144:147], v[212:215], v[92:95]
	v_mfma_f32_16x16x32_bf16 v[80:83], v[136:139], v[220:223], v[80:83]
	v_mfma_f32_16x16x32_bf16 v[76:79], v[144:147], v[220:223], v[76:79]
	s_setprio 0
	s_setprio 1
	v_mfma_f32_16x16x32_bf16 v[120:123], v[148:151], v[164:167], v[120:123]
	v_mfma_f32_16x16x32_bf16 v[116:119], v[156:159], v[164:167], v[116:119]
	v_mfma_f32_16x16x32_bf16 v[104:107], v[148:151], v[186:189], v[104:107]
	v_mfma_f32_16x16x32_bf16 v[100:103], v[156:159], v[186:189], v[100:103]
	v_mfma_f32_16x16x32_bf16 v[88:91], v[148:151], v[208:211], v[88:91]
	v_mfma_f32_16x16x32_bf16 v[84:87], v[156:159], v[208:211], v[84:87]
	v_mfma_f32_16x16x32_bf16 v[72:75], v[148:151], v[216:219], v[72:75]
	v_mfma_f32_16x16x32_bf16 v[68:71], v[156:159], v[216:219], v[68:71]
	v_mfma_f32_16x16x32_bf16 v[120:123], v[152:155], v[182:185], v[120:123]
	v_mfma_f32_16x16x32_bf16 v[116:119], v[160:163], v[182:185], v[116:119]
	v_mfma_f32_16x16x32_bf16 v[104:107], v[152:155], v[190:193], v[104:107]
	v_mfma_f32_16x16x32_bf16 v[100:103], v[160:163], v[190:193], v[100:103]
	v_mfma_f32_16x16x32_bf16 v[88:91], v[152:155], v[212:215], v[88:91]
	v_mfma_f32_16x16x32_bf16 v[84:87], v[160:163], v[212:215], v[84:87]
	v_mfma_f32_16x16x32_bf16 v[72:75], v[152:155], v[220:223], v[72:75]
	v_mfma_f32_16x16x32_bf16 v[68:71], v[160:163], v[220:223], v[68:71]
	s_setprio 0
	s_barrier
	s_add_i32 s53, s53, s41
	v_lshl_add_u64 v[194:195], s[28:29], 0, v[168:169]
	s_mov_b32 m0, s53
	ds_read_b128 v[164:167], v205 offset:16384
	ds_read_b128 v[182:185], v205 offset:17408
	ds_read_b128 v[186:189], v205 offset:18432
	ds_read_b128 v[190:193], v205 offset:19456
	ds_read_b128 v[208:211], v205 offset:20480
	ds_read_b128 v[212:215], v205 offset:21504
	ds_read_b128 v[216:219], v205 offset:22528
	ds_read_b128 v[220:223], v205 offset:23552
	global_load_lds_dwordx4 v[194:195], off
	s_add_i32 m0, s53, 0x2000
	s_add_u32 s54, s28, 0x40000
	v_lshl_add_u64 v[202:203], s[28:29], 0, v[172:173]
	s_addc_u32 s55, s29, 0
	s_add_i32 s53, s56, s41
	global_load_lds_dwordx4 v[202:203], off
	v_lshl_add_u64 v[224:225], s[54:55], 0, v[168:169]
	s_mov_b32 m0, s53
	v_lshl_add_u64 v[226:227], s[30:31], 0, v[170:171]
	global_load_lds_dwordx4 v[224:225], off
	s_add_i32 m0, s53, 0x2000
	v_lshl_add_u64 v[224:225], s[54:55], 0, v[172:173]
	global_load_lds_dwordx4 v[224:225], off
	s_mov_b32 m0, s42
	v_lshl_add_u64 v[224:225], s[30:31], 0, v[0:1]
	global_load_lds_dwordx4 v[224:225], off
	s_mov_b32 m0, s43
	s_add_i32 s53, 0, 0x18000
	global_load_lds_dwordx4 v[226:227], off
	s_waitcnt vmcnt(8) lgkmcnt(0)
	s_barrier
; #define PG8_STAGE(bufoff, gbase, voff) do { _Pragma("unroll") for (int _i = 0; _i < 2; ++_i) \
;         __builtin_amdgcn_global_load_lds((const unsigned*)((const char*)(gbase) + (voff)[_i]), (PG8_LAS unsigned*)(lds + (bufoff) + ldsw + _i * 8192), 16, 0, 0); } while (0)
; #define PG8_LDA(dst, b, h) do { _Pragma("unroll") for (int m = 0; m < 4; ++m) _Pragma("unroll") for (int k = 0; k < 2; ++k) dst[m][k] = *(const PG8_LAS bf16x8*)(lds + PG8_SA(b, h) + aoff + m * 2048 + k * 1024); } while (0)
; #define PG8_LDB(dst, b, h) do { _Pragma("unroll") for (int n = 0; n < 2; ++n) _Pragma("unroll") for (int k = 0; k < 2; ++k) dst[n][k] = *(const PG8_LAS bf16x8*)(lds + PG8_SB(b, h) + boff + n * 2048 + k * 1024); } while (0)
; #define PG8_MMA(ai, bj, At, Bt) do { __builtin_amdgcn_s_setprio(1); _Pragma("unroll") for (int m = 0; m < 4; ++m) _Pragma("unroll") for (int n = 0; n < 2; ++n) _Pragma("unroll") for (int k = 0; k < 2; ++k) \
;         acc[ai][bj][m][n] = __builtin_amdgcn_mfma_f32_16x16x32_bf16(Bt[n][k], At[m][k], acc[ai][bj][m][n], 0, 0, 0); __builtin_amdgcn_s_setprio(0); } while (0)
; #define PG8_WAIT_V(n) asm volatile("s_waitcnt vmcnt(" #n ")" ::: "memory")
; #define PG8_WAIT_L(n) asm volatile("s_waitcnt lgkmcnt(" #n ")" ::: "memory")
; #define PG8_BAR __builtin_amdgcn_s_barrier()
; #define PG8_SCHED __builtin_amdgcn_sched_barrier(0)
; template <class Epi, class Sched, bool ALIGN_EPI = false, bool SP2 = false>
; __device__ __forceinline__ void gemm_phase(PG8_LAS unsigned char* lds, const Gemm g, const Sched& S, const Epi& E) {
;     ...
;             PG8_WAIT_V(8); PG8_WAIT_L(0); PG8_BAR; PG8_MMA(1, 0, At, B0); PG8_MMA(1, 1, At, B1); PG8_BAR; PG8_SCHED;
;             PG8_LDB(B0, 1, 0); PG8_LDB(B1, 1, 1); PG8_SCHED; PG8_LDA(At, 1, 0); PG8_STAGE(PG8_SA(0, 1), a2 + hstep, voffA);
;             PG8_WAIT_V(8); PG8_WAIT_L(0); PG8_BAR; PG8_MMA(0, 0, At, B0); PG8_MMA(0, 1, At, B1); PG8_BAR; PG8_SCHED;
	s_setprio 1
	v_mfma_f32_16x16x32_bf16 v[64:67], v[132:135], v[164:167], v[64:67]
	v_mfma_f32_16x16x32_bf16 v[60:63], v[140:143], v[164:167], v[60:63]
	v_mfma_f32_16x16x32_bf16 v[48:51], v[132:135], v[186:189], v[48:51]
	v_mfma_f32_16x16x32_bf16 v[44:47], v[140:143], v[186:189], v[44:47]
	v_mfma_f32_16x16x32_bf16 v[32:35], v[132:135], v[208:211], v[32:35]
	v_mfma_f32_16x16x32_bf16 v[28:31], v[140:143], v[208:211], v[28:31]
	v_mfma_f32_16x16x32_bf16 v[16:19], v[132:135], v[216:219], v[16:19]
	v_mfma_f32_16x16x32_bf16 v[12:15], v[140:143], v[216:219], v[12:15]
	v_mfma_f32_16x16x32_bf16 v[64:67], v[136:139], v[182:185], v[64:67]
	v_mfma_f32_16x16x32_bf16 v[60:63], v[144:147], v[182:185], v[60:63]
	v_mfma_f32_16x16x32_bf16 v[48:51], v[136:139], v[190:193], v[48:51]
	v_mfma_f32_16x16x32_bf16 v[44:47], v[144:147], v[190:193], v[44:47]
	v_mfma_f32_16x16x32_bf16 v[32:35], v[136:139], v[212:215], v[32:35]
	v_mfma_f32_16x16x32_bf16 v[28:31], v[144:147], v[212:215], v[28:31]
	v_mfma_f32_16x16x32_bf16 v[16:19], v[136:139], v[220:223], v[16:19]
	v_mfma_f32_16x16x32_bf16 v[12:15], v[144:147], v[220:223], v[12:15]
	s_setprio 0
	s_setprio 1
	v_mfma_f32_16x16x32_bf16 v[56:59], v[148:151], v[164:167], v[56:59]
	v_mfma_f32_16x16x32_bf16 v[52:55], v[156:159], v[164:167], v[52:55]
	v_mfma_f32_16x16x32_bf16 v[40:43], v[148:151], v[186:189], v[40:43]
	v_mfma_f32_16x16x32_bf16 v[36:39], v[156:159], v[186:189], v[36:39]
	v_mfma_f32_16x16x32_bf16 v[24:27], v[148:151], v[208:211], v[24:27]
	v_mfma_f32_16x16x32_bf16 v[20:23], v[156:159], v[208:211], v[20:23]
	v_mfma_f32_16x16x32_bf16 v[8:11], v[148:151], v[216:219], v[8:11]
	v_mfma_f32_16x16x32_bf16 v[4:7], v[156:159], v[216:219], v[4:7]
	v_mfma_f32_16x16x32_bf16 v[56:59], v[152:155], v[182:185], v[56:59]
	v_mfma_f32_16x16x32_bf16 v[52:55], v[160:163], v[182:185], v[52:55]
	v_mfma_f32_16x16x32_bf16 v[40:43], v[152:155], v[190:193], v[40:43]
	v_mfma_f32_16x16x32_bf16 v[36:39], v[160:163], v[190:193], v[36:39]
	v_mfma_f32_16x16x32_bf16 v[24:27], v[152:155], v[212:215], v[24:27]
	v_mfma_f32_16x16x32_bf16 v[20:23], v[160:163], v[212:215], v[20:23]
	v_mfma_f32_16x16x32_bf16 v[8:11], v[152:155], v[220:223], v[8:11]
	v_mfma_f32_16x16x32_bf16 v[4:7], v[160:163], v[220:223], v[4:7]
	s_setprio 0
	s_barrier
	s_add_i32 s54, 0, 0x1c000
	ds_read_b128 v[132:135], v204 offset:32768
	ds_read_b128 v[136:139], v204 offset:33792
	ds_read_b128 v[140:143], v204 offset:34816
	ds_read_b128 v[144:147], v204 offset:35840
	ds_read_b128 v[148:151], v204 offset:49152
	ds_read_b128 v[152:155], v204 offset:50176
	ds_read_b128 v[156:159], v204 offset:51200
	ds_read_b128 v[160:163], v204 offset:52224
	s_add_u32 s30, s30, 0x40000
	s_addc_u32 s31, s31, 0
	s_mov_b32 m0, s46
	v_lshl_add_u64 v[228:229], s[30:31], 0, v[0:1]
	ds_read_b128 v[164:167], v205 offset:32768
	ds_read_b128 v[182:185], v205 offset:33792
	ds_read_b128 v[186:189], v205 offset:34816
	ds_read_b128 v[190:193], v205 offset:35840
	ds_read_b128 v[208:211], v205 offset:36864
	ds_read_b128 v[212:215], v205 offset:37888
	ds_read_b128 v[216:219], v205 offset:38912
	ds_read_b128 v[220:223], v205 offset:39936
	global_load_lds_dwordx4 v[228:229], off
	s_mov_b32 m0, s47
	v_lshl_add_u64 v[228:229], s[30:31], 0, v[170:171]
	global_load_lds_dwordx4 v[228:229], off
	s_waitcnt vmcnt(8) lgkmcnt(0)
	s_barrier
	s_setprio 1
	v_mfma_f32_16x16x32_bf16 v[128:131], v[132:135], v[164:167], v[128:131]
	v_mfma_f32_16x16x32_bf16 v[124:127], v[140:143], v[164:167], v[124:127]
	v_mfma_f32_16x16x32_bf16 v[112:115], v[132:135], v[186:189], v[112:115]
	v_mfma_f32_16x16x32_bf16 v[108:111], v[140:143], v[186:189], v[108:111]
	v_mfma_f32_16x16x32_bf16 v[96:99], v[132:135], v[208:211], v[96:99]
	v_mfma_f32_16x16x32_bf16 v[92:95], v[140:143], v[208:211], v[92:95]
	v_mfma_f32_16x16x32_bf16 v[80:83], v[132:135], v[216:219], v[80:83]
	v_mfma_f32_16x16x32_bf16 v[76:79], v[140:143], v[216:219], v[76:79]
	v_mfma_f32_16x16x32_bf16 v[128:131], v[136:139], v[182:185], v[128:131]
	v_mfma_f32_16x16x32_bf16 v[124:127], v[144:147], v[182:185], v[124:127]
	v_mfma_f32_16x16x32_bf16 v[112:115], v[136:139], v[190:193], v[112:115]
	v_mfma_f32_16x16x32_bf16 v[108:111], v[144:147], v[190:193], v[108:111]
	v_mfma_f32_16x16x32_bf16 v[96:99], v[136:139], v[212:215], v[96:99]
	v_mfma_f32_16x16x32_bf16 v[92:95], v[144:147], v[212:215], v[92:95]
	v_mfma_f32_16x16x32_bf16 v[80:83], v[136:139], v[220:223], v[80:83]
	v_mfma_f32_16x16x32_bf16 v[76:79], v[144:147], v[220:223], v[76:79]
	s_setprio 0
	s_setprio 1
	v_mfma_f32_16x16x32_bf16 v[120:123], v[148:151], v[164:167], v[120:123]
	v_mfma_f32_16x16x32_bf16 v[116:119], v[156:159], v[164:167], v[116:119]
	v_mfma_f32_16x16x32_bf16 v[104:107], v[148:151], v[186:189], v[104:107]
	v_mfma_f32_16x16x32_bf16 v[100:103], v[156:159], v[186:189], v[100:103]
	v_mfma_f32_16x16x32_bf16 v[88:91], v[148:151], v[208:211], v[88:91]
	v_mfma_f32_16x16x32_bf16 v[84:87], v[156:159], v[208:211], v[84:87]
	v_mfma_f32_16x16x32_bf16 v[72:75], v[148:151], v[216:219], v[72:75]
	v_mfma_f32_16x16x32_bf16 v[68:71], v[156:159], v[216:219], v[68:71]
	v_mfma_f32_16x16x32_bf16 v[120:123], v[152:155], v[182:185], v[120:123]
	v_mfma_f32_16x16x32_bf16 v[116:119], v[160:163], v[182:185], v[116:119]
	v_mfma_f32_16x16x32_bf16 v[104:107], v[152:155], v[190:193], v[104:107]
	v_mfma_f32_16x16x32_bf16 v[100:103], v[160:163], v[190:193], v[100:103]
	v_mfma_f32_16x16x32_bf16 v[88:91], v[152:155], v[212:215], v[88:91]
	v_mfma_f32_16x16x32_bf16 v[84:87], v[160:163], v[212:215], v[84:87]
	v_mfma_f32_16x16x32_bf16 v[72:75], v[152:155], v[220:223], v[72:75]
	v_mfma_f32_16x16x32_bf16 v[68:71], v[160:163], v[220:223], v[68:71]
	s_setprio 0
	s_barrier
; #define PG8_STAGE(bufoff, gbase, voff) do { _Pragma("unroll") for (int _i = 0; _i < 2; ++_i) \
;         __builtin_amdgcn_global_load_lds((const unsigned*)((const char*)(gbase) + (voff)[_i]), (PG8_LAS unsigned*)(lds + (bufoff) + ldsw + _i * 8192), 16, 0, 0); } while (0)
; #define PG8_LDA(dst, b, h) do { _Pragma("unroll") for (int m = 0; m < 4; ++m) _Pragma("unroll") for (int k = 0; k < 2; ++k) dst[m][k] = *(const PG8_LAS bf16x8*)(lds + PG8_SA(b, h) + aoff + m * 2048 + k * 1024); } while (0)
; #define PG8_MMA(ai, bj, At, Bt) do { __builtin_amdgcn_s_setprio(1); _Pragma("unroll") for (int m = 0; m < 4; ++m) _Pragma("unroll") for (int n = 0; n < 2; ++n) _Pragma("unroll") for (int k = 0; k < 2; ++k) \
;         acc[ai][bj][m][n] = __builtin_amdgcn_mfma_f32_16x16x32_bf16(Bt[n][k], At[m][k], acc[ai][bj][m][n], 0, 0, 0); __builtin_amdgcn_s_setprio(0); } while (0)
; #define PG8_WAIT_V(n) asm volatile("s_waitcnt vmcnt(" #n ")" ::: "memory")
; #define PG8_WAIT_L(n) asm volatile("s_waitcnt lgkmcnt(" #n ")" ::: "memory")
; #define PG8_BAR __builtin_amdgcn_s_barrier()
; #define PG8_SCHED __builtin_amdgcn_sched_barrier(0)
; template <class Epi, class Sched, bool ALIGN_EPI = false, bool SP2 = false>
; __device__ __forceinline__ void gemm_phase(PG8_LAS unsigned char* lds, const Gemm g, const Sched& S, const Epi& E) {
;     ...
;             PG8_LDA(At, 1, 1); PG8_STAGE(PG8_SB(1, 0), b3, voffB); PG8_STAGE(PG8_SB(1, 1), b3 + hstep, voffB); PG8_STAGE(PG8_SA(1, 0), a3, voffA);
;             PG8_WAIT_V(8); PG8_WAIT_L(0); PG8_BAR; PG8_MMA(1, 0, At, B0); PG8_MMA(1, 1, At, B1); PG8_BAR; PG8_SCHED;
	s_add_i32 s30, s53, s41
	s_add_i32 m0, s30, 0xffffff80
	ds_read_b128 v[164:167], v205 offset:49152
	ds_read_b128 v[182:185], v205 offset:50176
	ds_read_b128 v[186:189], v205 offset:51200
	ds_read_b128 v[190:193], v205 offset:52224
	ds_read_b128 v[208:211], v205 offset:53248
	ds_read_b128 v[212:215], v205 offset:54272
	ds_read_b128 v[216:219], v205 offset:55296
	ds_read_b128 v[220:223], v205 offset:56320
	global_load_lds_dwordx4 v[194:195], off offset:128
	s_add_i32 m0, s30, 0x1f80
	s_add_u32 s28, s28, 0x40080
	s_addc_u32 s29, s29, 0
	s_add_i32 s30, s54, s41
	global_load_lds_dwordx4 v[202:203], off offset:128
	s_mov_b32 m0, s30
	v_lshl_add_u64 v[194:195], s[28:29], 0, v[168:169]
	global_load_lds_dwordx4 v[194:195], off
	s_add_i32 m0, s30, 0x2000
	v_lshl_add_u64 v[194:195], s[28:29], 0, v[172:173]
	global_load_lds_dwordx4 v[194:195], off
	s_add_i32 m0, s50, 0xffffff80
	s_add_u32 s8, s8, 0x100
	s_addc_u32 s9, s9, 0
	global_load_lds_dwordx4 v[224:225], off offset:128
	s_add_i32 m0, s51, 0xffffff80
	s_add_u32 s23, s23, 0x100
	s_addc_u32 s44, s44, 0
	global_load_lds_dwordx4 v[226:227], off offset:128
	s_waitcnt vmcnt(8) lgkmcnt(0)
	s_barrier
	s_setprio 1
	v_mfma_f32_16x16x32_bf16 v[64:67], v[132:135], v[164:167], v[64:67]
	v_mfma_f32_16x16x32_bf16 v[60:63], v[140:143], v[164:167], v[60:63]
	v_mfma_f32_16x16x32_bf16 v[48:51], v[132:135], v[186:189], v[48:51]
	v_mfma_f32_16x16x32_bf16 v[44:47], v[140:143], v[186:189], v[44:47]
	v_mfma_f32_16x16x32_bf16 v[32:35], v[132:135], v[208:211], v[32:35]
	v_mfma_f32_16x16x32_bf16 v[28:31], v[140:143], v[208:211], v[28:31]
	v_mfma_f32_16x16x32_bf16 v[16:19], v[132:135], v[216:219], v[16:19]
	v_mfma_f32_16x16x32_bf16 v[12:15], v[140:143], v[216:219], v[12:15]
	v_mfma_f32_16x16x32_bf16 v[64:67], v[136:139], v[182:185], v[64:67]
	v_mfma_f32_16x16x32_bf16 v[60:63], v[144:147], v[182:185], v[60:63]
	v_mfma_f32_16x16x32_bf16 v[48:51], v[136:139], v[190:193], v[48:51]
	v_mfma_f32_16x16x32_bf16 v[44:47], v[144:147], v[190:193], v[44:47]
	v_mfma_f32_16x16x32_bf16 v[32:35], v[136:139], v[212:215], v[32:35]
	v_mfma_f32_16x16x32_bf16 v[28:31], v[144:147], v[212:215], v[28:31]
	v_mfma_f32_16x16x32_bf16 v[16:19], v[136:139], v[220:223], v[16:19]
	v_mfma_f32_16x16x32_bf16 v[12:15], v[144:147], v[220:223], v[12:15]
	s_setprio 0
	s_setprio 1
	v_mfma_f32_16x16x32_bf16 v[56:59], v[148:151], v[164:167], v[56:59]
	v_mfma_f32_16x16x32_bf16 v[52:55], v[156:159], v[164:167], v[52:55]
	v_mfma_f32_16x16x32_bf16 v[40:43], v[148:151], v[186:189], v[40:43]
	v_mfma_f32_16x16x32_bf16 v[36:39], v[156:159], v[186:189], v[36:39]
	v_mfma_f32_16x16x32_bf16 v[24:27], v[148:151], v[208:211], v[24:27]
	v_mfma_f32_16x16x32_bf16 v[20:23], v[156:159], v[208:211], v[20:23]
	v_mfma_f32_16x16x32_bf16 v[8:11], v[148:151], v[216:219], v[8:11]
	v_mfma_f32_16x16x32_bf16 v[4:7], v[156:159], v[216:219], v[4:7]
	v_mfma_f32_16x16x32_bf16 v[56:59], v[152:155], v[182:185], v[56:59]
	v_mfma_f32_16x16x32_bf16 v[52:55], v[160:163], v[182:185], v[52:55]
	v_mfma_f32_16x16x32_bf16 v[40:43], v[152:155], v[190:193], v[40:43]
	v_mfma_f32_16x16x32_bf16 v[36:39], v[160:163], v[190:193], v[36:39]
	v_mfma_f32_16x16x32_bf16 v[24:27], v[152:155], v[212:215], v[24:27]
	v_mfma_f32_16x16x32_bf16 v[20:23], v[160:163], v[212:215], v[20:23]
	v_mfma_f32_16x16x32_bf16 v[8:11], v[152:155], v[220:223], v[8:11]
	v_mfma_f32_16x16x32_bf16 v[4:7], v[160:163], v[220:223], v[4:7]
	s_setprio 0
	s_barrier
	s_add_i32 s45, s45, 2
	s_cmp_gt_u32 s45, 13
	s_cbranch_scc0 .LBB0_100
	s_and_b64 vcc, exec, s[14:15]
	s_cbranch_vccz .LBB0_103
	s_barrier

; __device__ __forceinline__ int opaque_tid() { int t = (int)threadIdx.x; asm volatile("" : "+v"(t)); return t; }
; #define PG8_STAGE(bufoff, gbase, voff) do { _Pragma("unroll") for (int _i = 0; _i < 2; ++_i) \
;         __builtin_amdgcn_global_load_lds((const unsigned*)((const char*)(gbase) + (voff)[_i]), (PG8_LAS unsigned*)(lds + (bufoff) + ldsw + _i * 8192), 16, 0, 0); } while (0)
; #define PG8_WAIT_V(n) asm volatile("s_waitcnt vmcnt(" #n ")" ::: "memory")
; #define PG8_BAR __builtin_amdgcn_s_barrier()
; template <class Epi, class Sched, bool ALIGN_EPI = false, bool SP2 = false>
; __device__ __forceinline__ void gemm_phase(PG8_LAS unsigned char* lds, const Gemm g, const Sched& S, const Epi& E) {
;     const int tid = opaque_tid(), wid = __builtin_amdgcn_readfirstlane(tid >> 6), lane = tid & 63, wr = wid >> 2, wc = wid & 3, fr = lane & 15, fq = lane >> 4;
;     const int K = g.K, nt = K / BK;
;     unsigned voffA[2], voffB[2];
; #pragma unroll
;     for (int i = 0; i < 2; ++i) { int R, C; stage_rc(tid * 16 + i * 8192, R, C); const int Rb = Epi::PERM ? ((R & ~31) + perm32(R & 31)) : R;
;         voffA[i] = (unsigned)(R * K + C) * 2u; voffB[i] = (unsigned)(Rb * K + C) * 2u; }
;     const size_t kstep = (size_t)(BK * 2);
;     const size_t hstep = (size_t)HALF * K * 2;
;     const size_t tstep = 2 * hstep;
;     const unsigned ldsw = (unsigned)wid * 1024u;
;     const int aoff = lds_byte(wr * 64 + fr, fq * 8), boff = lds_byte(wc * 32 + fr, fq * 8);
;     ...
;     if constexpr (SP2) {
;         PG8_STAGE(PG8_SB(0, 0), cB, voffB); PG8_STAGE(PG8_SB(0, 1), cB + hstep, voffB); PG8_STAGE(PG8_SA(0, 0), cA, voffA); PG8_STAGE(PG8_SA(0, 1), cA + hstep, voffA);
;         if (wr == 1) PG8_BAR;
;         PG8_WAIT_V(2); PG8_BAR;
;         PG8_STAGE(PG8_SB(1, 0), cB + kstep, voffB); PG8_STAGE(PG8_SA(1, 0), cA + kstep, voffA); PG8_STAGE(PG8_SB(1, 1), cB + hstep + kstep, voffB);
;         PG8_WAIT_V(6); PG8_BAR;
.LBB0_319:
	s_add_u32 s10, s4, 0x6400000
	s_addc_u32 s11, s5, 0
	s_add_u32 s12, s4, 0x1a600000
	s_addc_u32 s13, s5, 0
	s_and_b32 s48, s6, 3
	s_add_i32 m0, s42, 0x18000
	v_lshl_add_u64 v[10:11], v[10:11], 0, s[82:83]
	s_lshl_b32 s6, s7, 13
	s_lshl_b32 s14, s48, 12
	s_waitcnt vmcnt(2)
	s_barrier
	global_load_lds_dwordx4 v[10:11], off
	v_lshl_add_u64 v[8:9], v[8:9], 0, s[82:83]
	s_add_i32 m0, s42, 0x1a000
	s_add_i32 s49, s42, 0x8000
	s_add_i32 s50, s42, 0xa000
	global_load_lds_dwordx4 v[8:9], off
	v_lshl_add_u64 v[4:5], v[4:5], 0, s[82:83]
	s_mov_b32 m0, s49
	s_add_u32 s4, s30, 0x40080
	global_load_lds_dwordx4 v[4:5], off
	v_lshl_add_u64 v[4:5], v[6:7], 0, s[82:83]
	s_mov_b32 m0, s50
	s_addc_u32 s5, s31, 0
	global_load_lds_dwordx4 v[4:5], off
	s_add_i32 m0, s42, 0x1c000
	v_lshl_add_u64 v[4:5], s[4:5], 0, v[202:203]
	global_load_lds_dwordx4 v[4:5], off
	v_lshl_add_u64 v[4:5], s[4:5], 0, v[206:207]
	s_add_i32 m0, s42, 0x1e000
	s_cmpk_lt_u32 s3, 0x100
	global_load_lds_dwordx4 v[4:5], off
	v_bfe_u32 v4, v12, 4, 2
	v_and_b32_e32 v5, 15, v12
	v_lshlrev_b32_e32 v7, 4, v4
	v_lshl_or_b32 v3, s7, 6, v5
	v_lshlrev_b32_e32 v6, 3, v4
	v_lshl_or_b32 v5, v5, 6, v7
	v_lshlrev_b32_e32 v7, 2, v12
	v_cmp_eq_u32_e64 s[4:5], 0, v4
	v_lshlrev_b32_e32 v4, 14, v13
	v_and_b32_e32 v7, 32, v7
	v_and_b32_e32 v4, 0xffff8000, v4
	v_bitop3_b32 v8, v5, s6, v7 bitop3:0xde
	v_bitop3_b32 v251, v5, s14, v7 bitop3:0xde
	v_add_u32_e32 v251, 0x10000, v251
	v_lshl_add_u32 v4, v14, 11, v4
	v_and_b32_e32 v5, 1, v13
	v_lshl_or_b32 v4, v5, 6, v4
	v_lshl_add_u32 v208, v15, 1, v4
	v_lshlrev_b32_e32 v4, 14, v16
	v_and_b32_e32 v4, 0xffff8000, v4
	s_waitcnt vmcnt(6)
	v_lshl_add_u32 v4, v17, 11, v4
	v_and_b32_e32 v5, 1, v16
	v_lshl_or_b32 v4, v5, 6, v4
	v_lshl_or_b32 v252, s48, 5, v6
	s_cselect_b64 s[14:15], -1, 0
	s_mov_b32 s72, 0
	s_ashr_i32 s51, s36, 31
	v_mov_b32_e32 v209, v2
	v_lshl_add_u32 v210, v18, 1, v4
	v_mov_b32_e32 v211, v2
	v_add_u32_e32 v253, 0, v8
	s_barrier
	s_branch .LBB0_322

; #define PG8_STAGE(bufoff, gbase, voff) do { _Pragma("unroll") for (int _i = 0; _i < 2; ++_i) \
;         __builtin_amdgcn_global_load_lds((const unsigned*)((const char*)(gbase) + (voff)[_i]), (PG8_LAS unsigned*)(lds + (bufoff) + ldsw + _i * 8192), 16, 0, 0); } while (0)
; #define PG8_LDA(dst, b, h) do { _Pragma("unroll") for (int m = 0; m < 4; ++m) _Pragma("unroll") for (int k = 0; k < 2; ++k) dst[m][k] = *(const PG8_LAS bf16x8*)(lds + PG8_SA(b, h) + aoff + m * 2048 + k * 1024); } while (0)
; #define PG8_LDB(dst, b, h) do { _Pragma("unroll") for (int n = 0; n < 2; ++n) _Pragma("unroll") for (int k = 0; k < 2; ++k) dst[n][k] = *(const PG8_LAS bf16x8*)(lds + PG8_SB(b, h) + boff + n * 2048 + k * 1024); } while (0)
; #define PG8_MMA(ai, bj, At, Bt) do { __builtin_amdgcn_s_setprio(1); _Pragma("unroll") for (int m = 0; m < 4; ++m) _Pragma("unroll") for (int n = 0; n < 2; ++n) _Pragma("unroll") for (int k = 0; k < 2; ++k) \
;         acc[ai][bj][m][n] = __builtin_amdgcn_mfma_f32_16x16x32_bf16(Bt[n][k], At[m][k], acc[ai][bj][m][n], 0, 0, 0); __builtin_amdgcn_s_setprio(0); } while (0)
; #define PG8_WAIT_V(n) asm volatile("s_waitcnt vmcnt(" #n ")" ::: "memory")
; #define PG8_WAIT_L(n) asm volatile("s_waitcnt lgkmcnt(" #n ")" ::: "memory")
; #define PG8_BAR __builtin_amdgcn_s_barrier()
; template <class Epi, class Sched, bool ALIGN_EPI = false, bool SP2 = false>
; __device__ __forceinline__ void gemm_phase(PG8_LAS unsigned char* lds, const Gemm g, const Sched& S, const Epi& E) {
;     ...
;             const char* a1 = cA + (size_t)(t + 1) * kstep;
;             const char* a2 = last ? nA : cA + (size_t)(t + 2) * kstep; const char* b2 = last ? nB : cB + (size_t)(t + 2) * kstep;
;             const char* a3 = a2 + kstep; const char* b3 = b2 + kstep;
;             if (last && has_next) S.a_ready(nxt);
;             if constexpr (SP2) {
;             PG8_LDB(B0, 0, 0); PG8_LDB(B1, 0, 1); PG8_SCHED; PG8_LDA(At, 0, 0); PG8_STAGE(PG8_SA(1, 1), a1 + hstep, voffA);
;             PG8_WAIT_V(8); PG8_WAIT_L(0); PG8_BAR; PG8_MMA(0, 0, At, B0); PG8_MMA(0, 1, At, B1); PG8_BAR; PG8_SCHED;
;             PG8_LDA(At, 0, 1); PG8_STAGE(PG8_SB(0, 0), b2, voffB); PG8_STAGE(PG8_SB(0, 1), b2 + hstep, voffB); PG8_STAGE(PG8_SA(0, 0), a2, voffA);
;             PG8_WAIT_V(8); PG8_WAIT_L(0); PG8_BAR; PG8_MMA(1, 0, At, B0); PG8_MMA(1, 1, At, B1); PG8_BAR; PG8_SCHED;
.LBB0_329:
	s_add_u32 s30, s28, 0xfffc0080
	s_addc_u32 s31, s29, -1
	s_add_i32 s52, 0, 0x10000
	s_cmp_eq_u32 s45, 12
	s_cselect_b32 s35, s3, s31
	s_cselect_b32 s34, s17, s30
	s_cselect_b32 s31, s19, s44
	s_cselect_b32 s30, s25, s27
	s_add_i32 s54, 0, 0x14000
	ds_read_b128 v[108:111], v251
	ds_read_b128 v[112:115], v251 offset:1024
	ds_read_b128 v[124:127], v251 offset:2048
	ds_read_b128 v[128:131], v251 offset:3072
	ds_read_b128 v[132:135], v251 offset:16384
	ds_read_b128 v[140:143], v251 offset:17408
	ds_read_b128 v[148:151], v251 offset:18432
	ds_read_b128 v[156:159], v251 offset:19456
	v_lshl_add_u64 v[212:213], s[28:29], 0, v[208:209]
	s_add_i32 m0, s42, 0xc000
	ds_read_b128 v[164:167], v253
	ds_read_b128 v[168:171], v253 offset:1024
	ds_read_b128 v[172:175], v253 offset:2048
	ds_read_b128 v[176:179], v253 offset:3072
	ds_read_b128 v[180:183], v253 offset:4096
	ds_read_b128 v[184:187], v253 offset:5120
	ds_read_b128 v[188:191], v253 offset:6144
	ds_read_b128 v[192:195], v253 offset:7168
	global_load_lds_dwordx4 v[212:213], off
	s_add_i32 m0, s42, 0xe000
	v_lshl_add_u64 v[212:213], s[28:29], 0, v[210:211]
	global_load_lds_dwordx4 v[212:213], off
	s_waitcnt vmcnt(8) lgkmcnt(0)
	s_barrier
	s_setprio 1
	v_mfma_f32_16x16x32_bf16 v[160:163], v[108:111], v[164:167], v[160:163]
	v_mfma_f32_16x16x32_bf16 v[152:155], v[124:127], v[164:167], v[152:155]
	v_mfma_f32_16x16x32_bf16 v[120:123], v[108:111], v[172:175], v[120:123]
	v_mfma_f32_16x16x32_bf16 v[116:119], v[124:127], v[172:175], v[116:119]
	v_mfma_f32_16x16x32_bf16 v[96:99], v[108:111], v[180:183], v[96:99]
	v_mfma_f32_16x16x32_bf16 v[92:95], v[124:127], v[180:183], v[92:95]
	v_mfma_f32_16x16x32_bf16 v[80:83], v[108:111], v[188:191], v[80:83]
	v_mfma_f32_16x16x32_bf16 v[76:79], v[124:127], v[188:191], v[76:79]
	v_mfma_f32_16x16x32_bf16 v[160:163], v[112:115], v[168:171], v[160:163]
	v_mfma_f32_16x16x32_bf16 v[152:155], v[128:131], v[168:171], v[152:155]
	v_mfma_f32_16x16x32_bf16 v[120:123], v[112:115], v[176:179], v[120:123]
	v_mfma_f32_16x16x32_bf16 v[116:119], v[128:131], v[176:179], v[116:119]
	v_mfma_f32_16x16x32_bf16 v[96:99], v[112:115], v[184:187], v[96:99]
	v_mfma_f32_16x16x32_bf16 v[92:95], v[128:131], v[184:187], v[92:95]
	v_mfma_f32_16x16x32_bf16 v[80:83], v[112:115], v[192:195], v[80:83]
	v_mfma_f32_16x16x32_bf16 v[76:79], v[128:131], v[192:195], v[76:79]
	s_setprio 0
	s_setprio 1
	v_mfma_f32_16x16x32_bf16 v[144:147], v[132:135], v[164:167], v[144:147]
	v_mfma_f32_16x16x32_bf16 v[136:139], v[148:151], v[164:167], v[136:139]
	v_mfma_f32_16x16x32_bf16 v[104:107], v[132:135], v[172:175], v[104:107]
	v_mfma_f32_16x16x32_bf16 v[100:103], v[148:151], v[172:175], v[100:103]
	v_mfma_f32_16x16x32_bf16 v[88:91], v[132:135], v[180:183], v[88:91]
	v_mfma_f32_16x16x32_bf16 v[84:87], v[148:151], v[180:183], v[84:87]
	v_mfma_f32_16x16x32_bf16 v[72:75], v[132:135], v[188:191], v[72:75]
	v_mfma_f32_16x16x32_bf16 v[68:71], v[148:151], v[188:191], v[68:71]
	v_mfma_f32_16x16x32_bf16 v[144:147], v[140:143], v[168:171], v[144:147]
	v_mfma_f32_16x16x32_bf16 v[136:139], v[156:159], v[168:171], v[136:139]
	v_mfma_f32_16x16x32_bf16 v[104:107], v[140:143], v[176:179], v[104:107]
	v_mfma_f32_16x16x32_bf16 v[100:103], v[156:159], v[176:179], v[100:103]
	v_mfma_f32_16x16x32_bf16 v[88:91], v[140:143], v[184:187], v[88:91]
	v_mfma_f32_16x16x32_bf16 v[84:87], v[156:159], v[184:187], v[84:87]
	v_mfma_f32_16x16x32_bf16 v[72:75], v[140:143], v[192:195], v[72:75]
	v_mfma_f32_16x16x32_bf16 v[68:71], v[156:159], v[192:195], v[68:71]
	s_setprio 0
	s_barrier
	s_add_i32 s52, s52, s41
	v_lshl_add_u64 v[212:213], s[30:31], 0, v[202:203]
	s_mov_b32 m0, s52
	ds_read_b128 v[164:167], v253 offset:16384
	ds_read_b128 v[168:171], v253 offset:17408
	ds_read_b128 v[172:175], v253 offset:18432
	ds_read_b128 v[176:179], v253 offset:19456
	ds_read_b128 v[180:183], v253 offset:20480
	ds_read_b128 v[184:187], v253 offset:21504
	ds_read_b128 v[188:191], v253 offset:22528
	ds_read_b128 v[192:195], v253 offset:23552
	global_load_lds_dwordx4 v[212:213], off
	s_add_i32 m0, s52, 0x2000
	s_add_u32 s52, s30, 0x40000
	v_lshl_add_u64 v[214:215], s[30:31], 0, v[206:207]
	s_addc_u32 s53, s31, 0
	s_add_i32 s54, s54, s41
	global_load_lds_dwordx4 v[214:215], off
	v_lshl_add_u64 v[216:217], s[52:53], 0, v[202:203]
	s_mov_b32 m0, s54
	v_lshl_add_u64 v[218:219], s[34:35], 0, v[204:205]
	global_load_lds_dwordx4 v[216:217], off
	s_add_i32 m0, s54, 0x2000
	v_lshl_add_u64 v[216:217], s[52:53], 0, v[206:207]
	global_load_lds_dwordx4 v[216:217], off
	s_mov_b32 m0, s42
	v_lshl_add_u64 v[216:217], s[34:35], 0, v[0:1]
	global_load_lds_dwordx4 v[216:217], off
	s_mov_b32 m0, s43
	s_add_i32 s52, 0, 0x18000
	global_load_lds_dwordx4 v[218:219], off
	s_waitcnt vmcnt(8) lgkmcnt(0)
	s_barrier
; #define PG8_STAGE(bufoff, gbase, voff) do { _Pragma("unroll") for (int _i = 0; _i < 2; ++_i) \
;         __builtin_amdgcn_global_load_lds((const unsigned*)((const char*)(gbase) + (voff)[_i]), (PG8_LAS unsigned*)(lds + (bufoff) + ldsw + _i * 8192), 16, 0, 0); } while (0)
; #define PG8_LDA(dst, b, h) do { _Pragma("unroll") for (int m = 0; m < 4; ++m) _Pragma("unroll") for (int k = 0; k < 2; ++k) dst[m][k] = *(const PG8_LAS bf16x8*)(lds + PG8_SA(b, h) + aoff + m * 2048 + k * 1024); } while (0)
; #define PG8_LDB(dst, b, h) do { _Pragma("unroll") for (int n = 0; n < 2; ++n) _Pragma("unroll") for (int k = 0; k < 2; ++k) dst[n][k] = *(const PG8_LAS bf16x8*)(lds + PG8_SB(b, h) + boff + n * 2048 + k * 1024); } while (0)
; #define PG8_MMA(ai, bj, At, Bt) do { __builtin_amdgcn_s_setprio(1); _Pragma("unroll") for (int m = 0; m < 4; ++m) _Pragma("unroll") for (int n = 0; n < 2; ++n) _Pragma("unroll") for (int k = 0; k < 2; ++k) \
;         acc[ai][bj][m][n] = __builtin_amdgcn_mfma_f32_16x16x32_bf16(Bt[n][k], At[m][k], acc[ai][bj][m][n], 0, 0, 0); __builtin_amdgcn_s_setprio(0); } while (0)
; #define PG8_WAIT_V(n) asm volatile("s_waitcnt vmcnt(" #n ")" ::: "memory")
; #define PG8_WAIT_L(n) asm volatile("s_waitcnt lgkmcnt(" #n ")" ::: "memory")
; #define PG8_BAR __builtin_amdgcn_s_barrier()
; #define PG8_SCHED __builtin_amdgcn_sched_barrier(0)
; template <class Epi, class Sched, bool ALIGN_EPI = false, bool SP2 = false>
; __device__ __forceinline__ void gemm_phase(PG8_LAS unsigned char* lds, const Gemm g, const Sched& S, const Epi& E) {
;     ...
;             PG8_WAIT_V(8); PG8_WAIT_L(0); PG8_BAR; PG8_MMA(1, 0, At, B0); PG8_MMA(1, 1, At, B1); PG8_BAR; PG8_SCHED;
;             PG8_LDB(B0, 1, 0); PG8_LDB(B1, 1, 1); PG8_SCHED; PG8_LDA(At, 1, 0); PG8_STAGE(PG8_SA(0, 1), a2 + hstep, voffA);
;             PG8_WAIT_V(8); PG8_WAIT_L(0); PG8_BAR; PG8_MMA(0, 0, At, B0); PG8_MMA(0, 1, At, B1); PG8_BAR; PG8_SCHED;
	s_setprio 1
	v_mfma_f32_16x16x32_bf16 v[64:67], v[108:111], v[164:167], v[64:67]
	v_mfma_f32_16x16x32_bf16 v[60:63], v[124:127], v[164:167], v[60:63]
	v_mfma_f32_16x16x32_bf16 v[48:51], v[108:111], v[172:175], v[48:51]
	v_mfma_f32_16x16x32_bf16 v[44:47], v[124:127], v[172:175], v[44:47]
	v_mfma_f32_16x16x32_bf16 v[32:35], v[108:111], v[180:183], v[32:35]
	v_mfma_f32_16x16x32_bf16 v[28:31], v[124:127], v[180:183], v[28:31]
	v_mfma_f32_16x16x32_bf16 v[16:19], v[108:111], v[188:191], v[16:19]
	v_mfma_f32_16x16x32_bf16 v[12:15], v[124:127], v[188:191], v[12:15]
	v_mfma_f32_16x16x32_bf16 v[64:67], v[112:115], v[168:171], v[64:67]
	v_mfma_f32_16x16x32_bf16 v[60:63], v[128:131], v[168:171], v[60:63]
	v_mfma_f32_16x16x32_bf16 v[48:51], v[112:115], v[176:179], v[48:51]
	v_mfma_f32_16x16x32_bf16 v[44:47], v[128:131], v[176:179], v[44:47]
	v_mfma_f32_16x16x32_bf16 v[32:35], v[112:115], v[184:187], v[32:35]
	v_mfma_f32_16x16x32_bf16 v[28:31], v[128:131], v[184:187], v[28:31]
	v_mfma_f32_16x16x32_bf16 v[16:19], v[112:115], v[192:195], v[16:19]
	v_mfma_f32_16x16x32_bf16 v[12:15], v[128:131], v[192:195], v[12:15]
	s_setprio 0
	s_setprio 1
	v_mfma_f32_16x16x32_bf16 v[56:59], v[132:135], v[164:167], v[56:59]
	v_mfma_f32_16x16x32_bf16 v[52:55], v[148:151], v[164:167], v[52:55]
	v_mfma_f32_16x16x32_bf16 v[40:43], v[132:135], v[172:175], v[40:43]
	v_mfma_f32_16x16x32_bf16 v[36:39], v[148:151], v[172:175], v[36:39]
	v_mfma_f32_16x16x32_bf16 v[24:27], v[132:135], v[180:183], v[24:27]
	v_mfma_f32_16x16x32_bf16 v[20:23], v[148:151], v[180:183], v[20:23]
	v_mfma_f32_16x16x32_bf16 v[8:11], v[132:135], v[188:191], v[8:11]
	v_mfma_f32_16x16x32_bf16 v[4:7], v[148:151], v[188:191], v[4:7]
	v_mfma_f32_16x16x32_bf16 v[56:59], v[140:143], v[168:171], v[56:59]
	v_mfma_f32_16x16x32_bf16 v[52:55], v[156:159], v[168:171], v[52:55]
	v_mfma_f32_16x16x32_bf16 v[40:43], v[140:143], v[176:179], v[40:43]
	v_mfma_f32_16x16x32_bf16 v[36:39], v[156:159], v[176:179], v[36:39]
	v_mfma_f32_16x16x32_bf16 v[24:27], v[140:143], v[184:187], v[24:27]
	v_mfma_f32_16x16x32_bf16 v[20:23], v[156:159], v[184:187], v[20:23]
	v_mfma_f32_16x16x32_bf16 v[8:11], v[140:143], v[192:195], v[8:11]
	v_mfma_f32_16x16x32_bf16 v[4:7], v[156:159], v[192:195], v[4:7]
	s_setprio 0
	s_barrier
	s_add_i32 s53, 0, 0x1c000
	ds_read_b128 v[108:111], v251 offset:32768
	ds_read_b128 v[112:115], v251 offset:33792
	ds_read_b128 v[124:127], v251 offset:34816
	ds_read_b128 v[128:131], v251 offset:35840
	ds_read_b128 v[132:135], v251 offset:49152
	ds_read_b128 v[140:143], v251 offset:50176
	ds_read_b128 v[148:151], v251 offset:51200
	ds_read_b128 v[156:159], v251 offset:52224
	s_add_u32 s34, s34, 0x40000
	s_addc_u32 s35, s35, 0
	s_mov_b32 m0, s46
	v_lshl_add_u64 v[220:221], s[34:35], 0, v[0:1]
	ds_read_b128 v[164:167], v253 offset:32768
	ds_read_b128 v[168:171], v253 offset:33792
	ds_read_b128 v[172:175], v253 offset:34816
	ds_read_b128 v[176:179], v253 offset:35840
	ds_read_b128 v[180:183], v253 offset:36864
	ds_read_b128 v[184:187], v253 offset:37888
	ds_read_b128 v[188:191], v253 offset:38912
	ds_read_b128 v[192:195], v253 offset:39936
	global_load_lds_dwordx4 v[220:221], off
	s_mov_b32 m0, s47
	v_lshl_add_u64 v[220:221], s[34:35], 0, v[204:205]
	global_load_lds_dwordx4 v[220:221], off
	s_waitcnt vmcnt(8) lgkmcnt(0)
	s_barrier
	s_setprio 1
	v_mfma_f32_16x16x32_bf16 v[160:163], v[108:111], v[164:167], v[160:163]
	v_mfma_f32_16x16x32_bf16 v[152:155], v[124:127], v[164:167], v[152:155]
	v_mfma_f32_16x16x32_bf16 v[120:123], v[108:111], v[172:175], v[120:123]
	v_mfma_f32_16x16x32_bf16 v[116:119], v[124:127], v[172:175], v[116:119]
	v_mfma_f32_16x16x32_bf16 v[96:99], v[108:111], v[180:183], v[96:99]
	v_mfma_f32_16x16x32_bf16 v[92:95], v[124:127], v[180:183], v[92:95]
	v_mfma_f32_16x16x32_bf16 v[80:83], v[108:111], v[188:191], v[80:83]
	v_mfma_f32_16x16x32_bf16 v[76:79], v[124:127], v[188:191], v[76:79]
	v_mfma_f32_16x16x32_bf16 v[160:163], v[112:115], v[168:171], v[160:163]
	v_mfma_f32_16x16x32_bf16 v[152:155], v[128:131], v[168:171], v[152:155]
	v_mfma_f32_16x16x32_bf16 v[120:123], v[112:115], v[176:179], v[120:123]
	v_mfma_f32_16x16x32_bf16 v[116:119], v[128:131], v[176:179], v[116:119]
	v_mfma_f32_16x16x32_bf16 v[96:99], v[112:115], v[184:187], v[96:99]
	v_mfma_f32_16x16x32_bf16 v[92:95], v[128:131], v[184:187], v[92:95]
	v_mfma_f32_16x16x32_bf16 v[80:83], v[112:115], v[192:195], v[80:83]
	v_mfma_f32_16x16x32_bf16 v[76:79], v[128:131], v[192:195], v[76:79]
	s_setprio 0
	s_setprio 1
	v_mfma_f32_16x16x32_bf16 v[144:147], v[132:135], v[164:167], v[144:147]
	v_mfma_f32_16x16x32_bf16 v[136:139], v[148:151], v[164:167], v[136:139]
	v_mfma_f32_16x16x32_bf16 v[104:107], v[132:135], v[172:175], v[104:107]
	v_mfma_f32_16x16x32_bf16 v[100:103], v[148:151], v[172:175], v[100:103]
	v_mfma_f32_16x16x32_bf16 v[88:91], v[132:135], v[180:183], v[88:91]
	v_mfma_f32_16x16x32_bf16 v[84:87], v[148:151], v[180:183], v[84:87]
	v_mfma_f32_16x16x32_bf16 v[72:75], v[132:135], v[188:191], v[72:75]
	v_mfma_f32_16x16x32_bf16 v[68:71], v[148:151], v[188:191], v[68:71]
	v_mfma_f32_16x16x32_bf16 v[144:147], v[140:143], v[168:171], v[144:147]
	v_mfma_f32_16x16x32_bf16 v[136:139], v[156:159], v[168:171], v[136:139]
	v_mfma_f32_16x16x32_bf16 v[104:107], v[140:143], v[176:179], v[104:107]
	v_mfma_f32_16x16x32_bf16 v[100:103], v[156:159], v[176:179], v[100:103]
	v_mfma_f32_16x16x32_bf16 v[88:91], v[140:143], v[184:187], v[88:91]
	v_mfma_f32_16x16x32_bf16 v[84:87], v[156:159], v[184:187], v[84:87]
	v_mfma_f32_16x16x32_bf16 v[72:75], v[140:143], v[192:195], v[72:75]
	v_mfma_f32_16x16x32_bf16 v[68:71], v[156:159], v[192:195], v[68:71]
	s_setprio 0
	s_barrier
; #define PG8_STAGE(bufoff, gbase, voff) do { _Pragma("unroll") for (int _i = 0; _i < 2; ++_i) \
;         __builtin_amdgcn_global_load_lds((const unsigned*)((const char*)(gbase) + (voff)[_i]), (PG8_LAS unsigned*)(lds + (bufoff) + ldsw + _i * 8192), 16, 0, 0); } while (0)
; #define PG8_LDA(dst, b, h) do { _Pragma("unroll") for (int m = 0; m < 4; ++m) _Pragma("unroll") for (int k = 0; k < 2; ++k) dst[m][k] = *(const PG8_LAS bf16x8*)(lds + PG8_SA(b, h) + aoff + m * 2048 + k * 1024); } while (0)
; #define PG8_MMA(ai, bj, At, Bt) do { __builtin_amdgcn_s_setprio(1); _Pragma("unroll") for (int m = 0; m < 4; ++m) _Pragma("unroll") for (int n = 0; n < 2; ++n) _Pragma("unroll") for (int k = 0; k < 2; ++k) \
;         acc[ai][bj][m][n] = __builtin_amdgcn_mfma_f32_16x16x32_bf16(Bt[n][k], At[m][k], acc[ai][bj][m][n], 0, 0, 0); __builtin_amdgcn_s_setprio(0); } while (0)
; #define PG8_WAIT_V(n) asm volatile("s_waitcnt vmcnt(" #n ")" ::: "memory")
; #define PG8_WAIT_L(n) asm volatile("s_waitcnt lgkmcnt(" #n ")" ::: "memory")
; #define PG8_BAR __builtin_amdgcn_s_barrier()
; #define PG8_SCHED __builtin_amdgcn_sched_barrier(0)
; template <class Epi, class Sched, bool ALIGN_EPI = false, bool SP2 = false>
; __device__ __forceinline__ void gemm_phase(PG8_LAS unsigned char* lds, const Gemm g, const Sched& S, const Epi& E) {
;     ...
;         for (int t = 0; t < nt; t += 2) {
;             const bool last = (t == nt - 2);
;             const char* a1 = cA + (size_t)(t + 1) * kstep;
;             const char* a2 = last ? nA : cA + (size_t)(t + 2) * kstep; const char* b2 = last ? nB : cB + (size_t)(t + 2) * kstep;
;             const char* a3 = a2 + kstep; const char* b3 = b2 + kstep;
;             if (last && has_next) S.a_ready(nxt);
;     ...
;             PG8_LDA(At, 1, 1); PG8_STAGE(PG8_SB(1, 0), b3, voffB); PG8_STAGE(PG8_SB(1, 1), b3 + hstep, voffB); PG8_STAGE(PG8_SA(1, 0), a3, voffA);
;             PG8_WAIT_V(8); PG8_WAIT_L(0); PG8_BAR; PG8_MMA(1, 0, At, B0); PG8_MMA(1, 1, At, B1); PG8_BAR; PG8_SCHED;
	s_add_i32 s34, s52, s41
	s_add_i32 m0, s34, 0xffffff80
	ds_read_b128 v[164:167], v253 offset:49152
	ds_read_b128 v[168:171], v253 offset:50176
	ds_read_b128 v[172:175], v253 offset:51200
	ds_read_b128 v[176:179], v253 offset:52224
	ds_read_b128 v[180:183], v253 offset:53248
	ds_read_b128 v[184:187], v253 offset:54272
	ds_read_b128 v[188:191], v253 offset:55296
	ds_read_b128 v[192:195], v253 offset:56320
	global_load_lds_dwordx4 v[212:213], off offset:128
	s_add_i32 m0, s34, 0x1f80
	s_add_u32 s30, s30, 0x40080
	s_addc_u32 s31, s31, 0
	s_add_i32 s34, s53, s41
	global_load_lds_dwordx4 v[214:215], off offset:128
	s_mov_b32 m0, s34
	v_lshl_add_u64 v[212:213], s[30:31], 0, v[202:203]
	global_load_lds_dwordx4 v[212:213], off
	s_add_i32 m0, s34, 0x2000
	v_lshl_add_u64 v[212:213], s[30:31], 0, v[206:207]
	global_load_lds_dwordx4 v[212:213], off
	s_add_i32 m0, s49, 0xffffff80
	s_add_u32 s28, s28, 0x100
	s_addc_u32 s29, s29, 0
	global_load_lds_dwordx4 v[216:217], off offset:128
	s_add_i32 m0, s50, 0xffffff80
	s_add_u32 s27, s27, 0x100
	s_addc_u32 s44, s44, 0
	global_load_lds_dwordx4 v[218:219], off offset:128
	s_waitcnt vmcnt(8) lgkmcnt(0)
	s_barrier
	s_setprio 1
	v_mfma_f32_16x16x32_bf16 v[64:67], v[108:111], v[164:167], v[64:67]
	v_mfma_f32_16x16x32_bf16 v[60:63], v[124:127], v[164:167], v[60:63]
	v_mfma_f32_16x16x32_bf16 v[48:51], v[108:111], v[172:175], v[48:51]
	v_mfma_f32_16x16x32_bf16 v[44:47], v[124:127], v[172:175], v[44:47]
	v_mfma_f32_16x16x32_bf16 v[32:35], v[108:111], v[180:183], v[32:35]
	v_mfma_f32_16x16x32_bf16 v[28:31], v[124:127], v[180:183], v[28:31]
	v_mfma_f32_16x16x32_bf16 v[16:19], v[108:111], v[188:191], v[16:19]
	v_mfma_f32_16x16x32_bf16 v[12:15], v[124:127], v[188:191], v[12:15]
	v_mfma_f32_16x16x32_bf16 v[64:67], v[112:115], v[168:171], v[64:67]
	v_mfma_f32_16x16x32_bf16 v[60:63], v[128:131], v[168:171], v[60:63]
	v_mfma_f32_16x16x32_bf16 v[48:51], v[112:115], v[176:179], v[48:51]
	v_mfma_f32_16x16x32_bf16 v[44:47], v[128:131], v[176:179], v[44:47]
	v_mfma_f32_16x16x32_bf16 v[32:35], v[112:115], v[184:187], v[32:35]
	v_mfma_f32_16x16x32_bf16 v[28:31], v[128:131], v[184:187], v[28:31]
	v_mfma_f32_16x16x32_bf16 v[16:19], v[112:115], v[192:195], v[16:19]
	v_mfma_f32_16x16x32_bf16 v[12:15], v[128:131], v[192:195], v[12:15]
	s_setprio 0
	s_setprio 1
	v_mfma_f32_16x16x32_bf16 v[56:59], v[132:135], v[164:167], v[56:59]
	v_mfma_f32_16x16x32_bf16 v[52:55], v[148:151], v[164:167], v[52:55]
	v_mfma_f32_16x16x32_bf16 v[40:43], v[132:135], v[172:175], v[40:43]
	v_mfma_f32_16x16x32_bf16 v[36:39], v[148:151], v[172:175], v[36:39]
	v_mfma_f32_16x16x32_bf16 v[24:27], v[132:135], v[180:183], v[24:27]
	v_mfma_f32_16x16x32_bf16 v[20:23], v[148:151], v[180:183], v[20:23]
	v_mfma_f32_16x16x32_bf16 v[8:11], v[132:135], v[188:191], v[8:11]
	v_mfma_f32_16x16x32_bf16 v[4:7], v[148:151], v[188:191], v[4:7]
	v_mfma_f32_16x16x32_bf16 v[56:59], v[140:143], v[168:171], v[56:59]
	v_mfma_f32_16x16x32_bf16 v[52:55], v[156:159], v[168:171], v[52:55]
	v_mfma_f32_16x16x32_bf16 v[40:43], v[140:143], v[176:179], v[40:43]
	v_mfma_f32_16x16x32_bf16 v[36:39], v[156:159], v[176:179], v[36:39]
	v_mfma_f32_16x16x32_bf16 v[24:27], v[140:143], v[184:187], v[24:27]
	v_mfma_f32_16x16x32_bf16 v[20:23], v[156:159], v[184:187], v[20:23]
	v_mfma_f32_16x16x32_bf16 v[8:11], v[140:143], v[192:195], v[8:11]
	v_mfma_f32_16x16x32_bf16 v[4:7], v[156:159], v[192:195], v[4:7]
	s_setprio 0
	s_barrier
	s_add_i32 s45, s45, 2
	s_cmp_gt_u32 s45, 13
	s_cbranch_scc0 .LBB0_329
	s_and_b64 vcc, exec, s[14:15]
	s_cbranch_vccz .LBB0_332
	s_barrier

; __device__ __forceinline__ int opaque_tid() { int t = (int)threadIdx.x; asm volatile("" : "+v"(t)); return t; }
; #define PG8_STAGE(bufoff, gbase, voff) do { _Pragma("unroll") for (int _i = 0; _i < 2; ++_i) \
;         __builtin_amdgcn_global_load_lds((const unsigned*)((const char*)(gbase) + (voff)[_i]), (PG8_LAS unsigned*)(lds + (bufoff) + ldsw + _i * 8192), 16, 0, 0); } while (0)
; #define PG8_WAIT_V(n) asm volatile("s_waitcnt vmcnt(" #n ")" ::: "memory")
; #define PG8_BAR __builtin_amdgcn_s_barrier()
; template <class Epi, class Sched, bool ALIGN_EPI = false, bool SP2 = false>
; __device__ __forceinline__ void gemm_phase(PG8_LAS unsigned char* lds, const Gemm g, const Sched& S, const Epi& E) {
;     const int tid = opaque_tid(), wid = __builtin_amdgcn_readfirstlane(tid >> 6), lane = tid & 63, wr = wid >> 2, wc = wid & 3, fr = lane & 15, fq = lane >> 4;
;     const int K = g.K, nt = K / BK;
;     unsigned voffA[2], voffB[2];
; #pragma unroll
;     for (int i = 0; i < 2; ++i) { int R, C; stage_rc(tid * 16 + i * 8192, R, C); const int Rb = Epi::PERM ? ((R & ~31) + perm32(R & 31)) : R;
;         voffA[i] = (unsigned)(R * K + C) * 2u; voffB[i] = (unsigned)(Rb * K + C) * 2u; }
;     const size_t kstep = (size_t)(BK * 2);
;     const size_t hstep = (size_t)HALF * K * 2;
;     const size_t tstep = 2 * hstep;
;     const unsigned ldsw = (unsigned)wid * 1024u;
;     const int aoff = lds_byte(wr * 64 + fr, fq * 8), boff = lds_byte(wc * 32 + fr, fq * 8);
;     ...
;         PG8_STAGE(PG8_SB(0, 0), cB, voffB); PG8_STAGE(PG8_SB(0, 1), cB + hstep, voffB); PG8_STAGE(PG8_SA(0, 0), cA, voffA); PG8_STAGE(PG8_SA(0, 1), cA + hstep, voffA);
;         if (wr == 1) PG8_BAR;
;         PG8_WAIT_V(2); PG8_BAR;
;         PG8_STAGE(PG8_SB(1, 0), cB + kstep, voffB); PG8_STAGE(PG8_SA(1, 0), cA + kstep, voffA); PG8_STAGE(PG8_SB(1, 1), cB + hstep + kstep, voffB);
;         PG8_WAIT_V(6); PG8_BAR;
.LBB0_399:
	s_add_u32 s12, s4, 0xa400000
	s_addc_u32 s13, s5, 0
	s_lshl_b32 s3, s3, 5
	s_and_b32 s17, s3, 0x60
	s_add_i32 m0, s37, 0x18000
	v_lshl_add_u64 v[10:11], v[10:11], 0, s[82:83]
	s_lshl_b32 s7, s16, 13
	s_lshl_b32 s20, s17, 7
	s_waitcnt vmcnt(2)
	s_barrier
	global_load_lds_dwordx4 v[10:11], off
	v_lshl_add_u64 v[8:9], v[8:9], 0, s[82:83]
	s_add_i32 m0, s37, 0x1a000
	s_add_i32 s41, s37, 0x8000
	s_add_i32 s42, s37, 0xa000
	global_load_lds_dwordx4 v[8:9], off
	v_lshl_add_u64 v[4:5], v[4:5], 0, s[82:83]
	s_mov_b32 m0, s41
	s_add_u32 s18, s24, 0x40080
	global_load_lds_dwordx4 v[4:5], off
	v_lshl_add_u64 v[4:5], v[6:7], 0, s[82:83]
	s_mov_b32 m0, s42
	s_addc_u32 s19, s25, 0
	global_load_lds_dwordx4 v[4:5], off
	s_add_i32 m0, s37, 0x1c000
	v_lshl_add_u64 v[4:5], s[18:19], 0, v[134:135]
	global_load_lds_dwordx4 v[4:5], off
	v_lshl_add_u64 v[4:5], s[18:19], 0, v[0:1]
	s_add_i32 m0, s37, 0x1e000
	v_bfe_u32 v6, v12, 4, 2
	global_load_lds_dwordx4 v[4:5], off
	v_and_b32_e32 v5, 15, v12
	v_lshlrev_b32_e32 v4, 4, v6
	v_lshlrev_b32_e32 v7, 2, v12
	v_lshl_or_b32 v3, s16, 6, v5
	v_lshl_or_b32 v5, v5, 6, v4
	v_and_b32_e32 v7, 32, v7
	v_bitop3_b32 v8, v5, s7, v7 bitop3:0xde
	v_bitop3_b32 v164, v5, s20, v7 bitop3:0xde
	v_add_u32_e32 v164, 0x10000, v164
	v_mov_b32_e32 v5, v2
	v_lshl_add_u64 v[4:5], s[4:5], 0, v[4:5]
	s_mov_b64 s[4:5], 0x1a600000
	v_lshl_add_u64 v[138:139], v[4:5], 0, s[4:5]
	v_lshlrev_b32_e32 v4, 14, v17
	v_and_b32_e32 v4, 0xffff8000, v4
	v_lshl_add_u32 v4, v16, 11, v4
	v_and_b32_e32 v5, 1, v17
	v_lshl_or_b32 v4, v5, 6, v4
	v_lshl_add_u32 v140, v18, 1, v4
	v_lshlrev_b32_e32 v4, 14, v13
	v_and_b32_e32 v4, 0xffff8000, v4
	s_waitcnt vmcnt(6)
	v_lshl_add_u32 v4, v14, 11, v4
	v_and_b32_e32 v5, 1, v13
	s_cmpk_lt_u32 s15, 0x100
	v_lshl_or_b32 v4, v5, 6, v4
	s_sext_i32_i16 s3, s14
	s_cselect_b64 s[14:15], -1, 0
	v_lshl_or_b32 v165, v6, 3, s17
	v_mov_b32_e32 v141, v2
	v_lshl_add_u32 v142, v15, 1, v4
	v_mov_b32_e32 v143, v2
	s_mov_b32 s72, 0
	v_add_u32_e32 v166, 0, v8
	s_barrier
	s_branch .LBB0_402

; #define PG8_STAGE(bufoff, gbase, voff) do { _Pragma("unroll") for (int _i = 0; _i < 2; ++_i) \
;         __builtin_amdgcn_global_load_lds((const unsigned*)((const char*)(gbase) + (voff)[_i]), (PG8_LAS unsigned*)(lds + (bufoff) + ldsw + _i * 8192), 16, 0, 0); } while (0)
; #define PG8_LDA(dst, b, h) do { _Pragma("unroll") for (int m = 0; m < 4; ++m) _Pragma("unroll") for (int k = 0; k < 2; ++k) dst[m][k] = *(const PG8_LAS bf16x8*)(lds + PG8_SA(b, h) + aoff + m * 2048 + k * 1024); } while (0)
; #define PG8_LDB(dst, b, h) do { _Pragma("unroll") for (int n = 0; n < 2; ++n) _Pragma("unroll") for (int k = 0; k < 2; ++k) dst[n][k] = *(const PG8_LAS bf16x8*)(lds + PG8_SB(b, h) + boff + n * 2048 + k * 1024); } while (0)
; #define PG8_MMA(ai, bj, At, Bt) do { __builtin_amdgcn_s_setprio(1); _Pragma("unroll") for (int m = 0; m < 4; ++m) _Pragma("unroll") for (int n = 0; n < 2; ++n) _Pragma("unroll") for (int k = 0; k < 2; ++k) \
;         acc[ai][bj][m][n] = __builtin_amdgcn_mfma_f32_16x16x32_bf16(Bt[n][k], At[m][k], acc[ai][bj][m][n], 0, 0, 0); __builtin_amdgcn_s_setprio(0); } while (0)
; #define PG8_WAIT_V(n) asm volatile("s_waitcnt vmcnt(" #n ")" ::: "memory")
; #define PG8_WAIT_L(n) asm volatile("s_waitcnt lgkmcnt(" #n ")" ::: "memory")
; #define PG8_BAR __builtin_amdgcn_s_barrier()
; template <class Epi, class Sched, bool ALIGN_EPI = false, bool SP2 = false>
; __device__ __forceinline__ void gemm_phase(PG8_LAS unsigned char* lds, const Gemm g, const Sched& S, const Epi& E) {
;     ...
;             const char* a1 = cA + (size_t)(t + 1) * kstep;
;             const char* a2 = last ? nA : cA + (size_t)(t + 2) * kstep; const char* b2 = last ? nB : cB + (size_t)(t + 2) * kstep;
;             const char* a3 = a2 + kstep; const char* b3 = b2 + kstep;
;             if (last && has_next) S.a_ready(nxt);
;             if constexpr (SP2) {
;             PG8_LDB(B0, 0, 0); PG8_LDB(B1, 0, 1); PG8_SCHED; PG8_LDA(At, 0, 0); PG8_STAGE(PG8_SA(1, 1), a1 + hstep, voffA);
;             PG8_WAIT_V(8); PG8_WAIT_L(0); PG8_BAR; PG8_MMA(0, 0, At, B0); PG8_MMA(0, 1, At, B1); PG8_BAR; PG8_SCHED;
;             PG8_LDA(At, 0, 1); PG8_STAGE(PG8_SB(0, 0), b2, voffB); PG8_STAGE(PG8_SB(0, 1), b2 + hstep, voffB); PG8_STAGE(PG8_SA(0, 0), a2, voffA);
;             PG8_WAIT_V(8); PG8_WAIT_L(0); PG8_BAR; PG8_MMA(1, 0, At, B0); PG8_MMA(1, 1, At, B1); PG8_BAR; PG8_SCHED;
.LBB0_405:
	s_add_u32 s24, s8, 0xfffc0080
	s_addc_u32 s25, s9, -1
	s_add_i32 s47, 0, 0x10000
	s_cmp_eq_u32 s46, 12
	s_cselect_b32 s27, s7, s25
	s_cselect_b32 s26, s17, s24
	s_cselect_b32 s25, s19, s45
	s_cselect_b32 s24, s43, s44
	s_add_i32 s50, 0, 0x14000
	ds_read_b128 v[144:147], v164
	ds_read_b128 v[148:151], v164 offset:1024
	ds_read_b128 v[152:155], v164 offset:2048
	ds_read_b128 v[156:159], v164 offset:3072
	ds_read_b128 v[160:163], v164 offset:16384
	ds_read_b128 v[168:171], v164 offset:17408
	ds_read_b128 v[172:175], v164 offset:18432
	ds_read_b128 v[176:179], v164 offset:19456
	v_lshl_add_u64 v[198:199], s[8:9], 0, v[140:141]
	s_add_i32 m0, s37, 0xc000
	ds_read_b128 v[180:183], v166
	ds_read_b128 v[184:187], v166 offset:1024
	ds_read_b128 v[188:191], v166 offset:2048
	ds_read_b128 v[192:195], v166 offset:3072
	ds_read_b128 v[202:205], v166 offset:4096
	ds_read_b128 v[206:209], v166 offset:5120
	ds_read_b128 v[210:213], v166 offset:6144
	ds_read_b128 v[214:217], v166 offset:7168
	global_load_lds_dwordx4 v[198:199], off
	s_add_i32 m0, s37, 0xe000
	v_lshl_add_u64 v[198:199], s[8:9], 0, v[142:143]
	global_load_lds_dwordx4 v[198:199], off
	s_waitcnt vmcnt(8) lgkmcnt(0)
	s_barrier
	s_setprio 1
	v_mfma_f32_16x16x32_bf16 v[128:131], v[144:147], v[180:183], v[128:131]
	v_mfma_f32_16x16x32_bf16 v[120:123], v[152:155], v[180:183], v[120:123]
	v_mfma_f32_16x16x32_bf16 v[112:115], v[144:147], v[188:191], v[112:115]
	v_mfma_f32_16x16x32_bf16 v[104:107], v[152:155], v[188:191], v[104:107]
	v_mfma_f32_16x16x32_bf16 v[96:99], v[144:147], v[202:205], v[96:99]
	v_mfma_f32_16x16x32_bf16 v[88:91], v[152:155], v[202:205], v[88:91]
	v_mfma_f32_16x16x32_bf16 v[80:83], v[144:147], v[210:213], v[80:83]
	v_mfma_f32_16x16x32_bf16 v[72:75], v[152:155], v[210:213], v[72:75]
	v_mfma_f32_16x16x32_bf16 v[128:131], v[148:151], v[184:187], v[128:131]
	v_mfma_f32_16x16x32_bf16 v[120:123], v[156:159], v[184:187], v[120:123]
	v_mfma_f32_16x16x32_bf16 v[112:115], v[148:151], v[192:195], v[112:115]
	v_mfma_f32_16x16x32_bf16 v[104:107], v[156:159], v[192:195], v[104:107]
	v_mfma_f32_16x16x32_bf16 v[96:99], v[148:151], v[206:209], v[96:99]
	v_mfma_f32_16x16x32_bf16 v[88:91], v[156:159], v[206:209], v[88:91]
	v_mfma_f32_16x16x32_bf16 v[80:83], v[148:151], v[214:217], v[80:83]
	v_mfma_f32_16x16x32_bf16 v[72:75], v[156:159], v[214:217], v[72:75]
	s_setprio 0
	s_setprio 1
	v_mfma_f32_16x16x32_bf16 v[124:127], v[160:163], v[180:183], v[124:127]
	v_mfma_f32_16x16x32_bf16 v[116:119], v[172:175], v[180:183], v[116:119]
	v_mfma_f32_16x16x32_bf16 v[108:111], v[160:163], v[188:191], v[108:111]
	v_mfma_f32_16x16x32_bf16 v[100:103], v[172:175], v[188:191], v[100:103]
	v_mfma_f32_16x16x32_bf16 v[92:95], v[160:163], v[202:205], v[92:95]
	v_mfma_f32_16x16x32_bf16 v[84:87], v[172:175], v[202:205], v[84:87]
	v_mfma_f32_16x16x32_bf16 v[76:79], v[160:163], v[210:213], v[76:79]
	v_mfma_f32_16x16x32_bf16 v[68:71], v[172:175], v[210:213], v[68:71]
	v_mfma_f32_16x16x32_bf16 v[124:127], v[168:171], v[184:187], v[124:127]
	v_mfma_f32_16x16x32_bf16 v[116:119], v[176:179], v[184:187], v[116:119]
	v_mfma_f32_16x16x32_bf16 v[108:111], v[168:171], v[192:195], v[108:111]
	v_mfma_f32_16x16x32_bf16 v[100:103], v[176:179], v[192:195], v[100:103]
	v_mfma_f32_16x16x32_bf16 v[92:95], v[168:171], v[206:209], v[92:95]
	v_mfma_f32_16x16x32_bf16 v[84:87], v[176:179], v[206:209], v[84:87]
	v_mfma_f32_16x16x32_bf16 v[76:79], v[168:171], v[214:217], v[76:79]
	v_mfma_f32_16x16x32_bf16 v[68:71], v[176:179], v[214:217], v[68:71]
	s_setprio 0
	s_barrier
	s_add_i32 s47, s47, s35
	v_lshl_add_u64 v[198:199], s[24:25], 0, v[134:135]
	s_mov_b32 m0, s47
	ds_read_b128 v[180:183], v166 offset:16384
	ds_read_b128 v[184:187], v166 offset:17408
	ds_read_b128 v[188:191], v166 offset:18432
	ds_read_b128 v[192:195], v166 offset:19456
	ds_read_b128 v[202:205], v166 offset:20480
	ds_read_b128 v[206:209], v166 offset:21504
	ds_read_b128 v[210:213], v166 offset:22528
	ds_read_b128 v[214:217], v166 offset:23552
	global_load_lds_dwordx4 v[198:199], off
	s_add_i32 m0, s47, 0x2000
	s_add_u32 s48, s24, 0x40000
	v_lshl_add_u64 v[218:219], s[24:25], 0, v[0:1]
	s_addc_u32 s49, s25, 0
	s_add_i32 s47, s50, s35
	global_load_lds_dwordx4 v[218:219], off
	v_lshl_add_u64 v[220:221], s[48:49], 0, v[134:135]
	s_mov_b32 m0, s47
	v_lshl_add_u64 v[222:223], s[26:27], 0, v[132:133]
	global_load_lds_dwordx4 v[220:221], off
	s_add_i32 m0, s47, 0x2000
	v_lshl_add_u64 v[220:221], s[48:49], 0, v[0:1]
	global_load_lds_dwordx4 v[220:221], off
	s_mov_b32 m0, s37
	v_lshl_add_u64 v[220:221], s[26:27], 0, v[136:137]
	global_load_lds_dwordx4 v[220:221], off
	s_mov_b32 m0, s38
	s_add_i32 s47, 0, 0x18000
	global_load_lds_dwordx4 v[222:223], off
	s_waitcnt vmcnt(8) lgkmcnt(0)
	s_barrier
; #define PG8_STAGE(bufoff, gbase, voff) do { _Pragma("unroll") for (int _i = 0; _i < 2; ++_i) \
;         __builtin_amdgcn_global_load_lds((const unsigned*)((const char*)(gbase) + (voff)[_i]), (PG8_LAS unsigned*)(lds + (bufoff) + ldsw + _i * 8192), 16, 0, 0); } while (0)
; #define PG8_LDA(dst, b, h) do { _Pragma("unroll") for (int m = 0; m < 4; ++m) _Pragma("unroll") for (int k = 0; k < 2; ++k) dst[m][k] = *(const PG8_LAS bf16x8*)(lds + PG8_SA(b, h) + aoff + m * 2048 + k * 1024); } while (0)
; #define PG8_LDB(dst, b, h) do { _Pragma("unroll") for (int n = 0; n < 2; ++n) _Pragma("unroll") for (int k = 0; k < 2; ++k) dst[n][k] = *(const PG8_LAS bf16x8*)(lds + PG8_SB(b, h) + boff + n * 2048 + k * 1024); } while (0)
; #define PG8_MMA(ai, bj, At, Bt) do { __builtin_amdgcn_s_setprio(1); _Pragma("unroll") for (int m = 0; m < 4; ++m) _Pragma("unroll") for (int n = 0; n < 2; ++n) _Pragma("unroll") for (int k = 0; k < 2; ++k) \
;         acc[ai][bj][m][n] = __builtin_amdgcn_mfma_f32_16x16x32_bf16(Bt[n][k], At[m][k], acc[ai][bj][m][n], 0, 0, 0); __builtin_amdgcn_s_setprio(0); } while (0)
; #define PG8_WAIT_V(n) asm volatile("s_waitcnt vmcnt(" #n ")" ::: "memory")
; #define PG8_WAIT_L(n) asm volatile("s_waitcnt lgkmcnt(" #n ")" ::: "memory")
; #define PG8_BAR __builtin_amdgcn_s_barrier()
; #define PG8_SCHED __builtin_amdgcn_sched_barrier(0)
; template <class Epi, class Sched, bool ALIGN_EPI = false, bool SP2 = false>
; __device__ __forceinline__ void gemm_phase(PG8_LAS unsigned char* lds, const Gemm g, const Sched& S, const Epi& E) {
;     ...
;             PG8_WAIT_V(8); PG8_WAIT_L(0); PG8_BAR; PG8_MMA(1, 0, At, B0); PG8_MMA(1, 1, At, B1); PG8_BAR; PG8_SCHED;
;             PG8_LDB(B0, 1, 0); PG8_LDB(B1, 1, 1); PG8_SCHED; PG8_LDA(At, 1, 0); PG8_STAGE(PG8_SA(0, 1), a2 + hstep, voffA);
;             PG8_WAIT_V(8); PG8_WAIT_L(0); PG8_BAR; PG8_MMA(0, 0, At, B0); PG8_MMA(0, 1, At, B1); PG8_BAR; PG8_SCHED;
	s_setprio 1
	v_mfma_f32_16x16x32_bf16 v[64:67], v[144:147], v[180:183], v[64:67]
	v_mfma_f32_16x16x32_bf16 v[56:59], v[152:155], v[180:183], v[56:59]
	v_mfma_f32_16x16x32_bf16 v[48:51], v[144:147], v[188:191], v[48:51]
	v_mfma_f32_16x16x32_bf16 v[40:43], v[152:155], v[188:191], v[40:43]
	v_mfma_f32_16x16x32_bf16 v[32:35], v[144:147], v[202:205], v[32:35]
	v_mfma_f32_16x16x32_bf16 v[24:27], v[152:155], v[202:205], v[24:27]
	v_mfma_f32_16x16x32_bf16 v[16:19], v[144:147], v[210:213], v[16:19]
	v_mfma_f32_16x16x32_bf16 v[8:11], v[152:155], v[210:213], v[8:11]
	v_mfma_f32_16x16x32_bf16 v[64:67], v[148:151], v[184:187], v[64:67]
	v_mfma_f32_16x16x32_bf16 v[56:59], v[156:159], v[184:187], v[56:59]
	v_mfma_f32_16x16x32_bf16 v[48:51], v[148:151], v[192:195], v[48:51]
	v_mfma_f32_16x16x32_bf16 v[40:43], v[156:159], v[192:195], v[40:43]
	v_mfma_f32_16x16x32_bf16 v[32:35], v[148:151], v[206:209], v[32:35]
	v_mfma_f32_16x16x32_bf16 v[24:27], v[156:159], v[206:209], v[24:27]
	v_mfma_f32_16x16x32_bf16 v[16:19], v[148:151], v[214:217], v[16:19]
	v_mfma_f32_16x16x32_bf16 v[8:11], v[156:159], v[214:217], v[8:11]
	s_setprio 0
	s_setprio 1
	v_mfma_f32_16x16x32_bf16 v[60:63], v[160:163], v[180:183], v[60:63]
	v_mfma_f32_16x16x32_bf16 v[52:55], v[172:175], v[180:183], v[52:55]
	v_mfma_f32_16x16x32_bf16 v[44:47], v[160:163], v[188:191], v[44:47]
	v_mfma_f32_16x16x32_bf16 v[36:39], v[172:175], v[188:191], v[36:39]
	v_mfma_f32_16x16x32_bf16 v[28:31], v[160:163], v[202:205], v[28:31]
	v_mfma_f32_16x16x32_bf16 v[20:23], v[172:175], v[202:205], v[20:23]
	v_mfma_f32_16x16x32_bf16 v[12:15], v[160:163], v[210:213], v[12:15]
	v_mfma_f32_16x16x32_bf16 v[4:7], v[172:175], v[210:213], v[4:7]
	v_mfma_f32_16x16x32_bf16 v[60:63], v[168:171], v[184:187], v[60:63]
	v_mfma_f32_16x16x32_bf16 v[52:55], v[176:179], v[184:187], v[52:55]
	v_mfma_f32_16x16x32_bf16 v[44:47], v[168:171], v[192:195], v[44:47]
	v_mfma_f32_16x16x32_bf16 v[36:39], v[176:179], v[192:195], v[36:39]
	v_mfma_f32_16x16x32_bf16 v[28:31], v[168:171], v[206:209], v[28:31]
	v_mfma_f32_16x16x32_bf16 v[20:23], v[176:179], v[206:209], v[20:23]
	v_mfma_f32_16x16x32_bf16 v[12:15], v[168:171], v[214:217], v[12:15]
	v_mfma_f32_16x16x32_bf16 v[4:7], v[176:179], v[214:217], v[4:7]
	s_setprio 0
	s_barrier
	s_add_i32 s48, 0, 0x1c000
	ds_read_b128 v[144:147], v164 offset:32768
	ds_read_b128 v[148:151], v164 offset:33792
	ds_read_b128 v[152:155], v164 offset:34816
	ds_read_b128 v[156:159], v164 offset:35840
	ds_read_b128 v[160:163], v164 offset:49152
	ds_read_b128 v[168:171], v164 offset:50176
	ds_read_b128 v[172:175], v164 offset:51200
	ds_read_b128 v[176:179], v164 offset:52224
	s_add_u32 s26, s26, 0x40000
	s_addc_u32 s27, s27, 0
	s_mov_b32 m0, s39
	v_lshl_add_u64 v[224:225], s[26:27], 0, v[136:137]
	ds_read_b128 v[180:183], v166 offset:32768
	ds_read_b128 v[184:187], v166 offset:33792
	ds_read_b128 v[188:191], v166 offset:34816
	ds_read_b128 v[192:195], v166 offset:35840
	ds_read_b128 v[202:205], v166 offset:36864
	ds_read_b128 v[206:209], v166 offset:37888
	ds_read_b128 v[210:213], v166 offset:38912
	ds_read_b128 v[214:217], v166 offset:39936
	global_load_lds_dwordx4 v[224:225], off
	s_mov_b32 m0, s40
	v_lshl_add_u64 v[224:225], s[26:27], 0, v[132:133]
	global_load_lds_dwordx4 v[224:225], off
	s_waitcnt vmcnt(8) lgkmcnt(0)
	s_barrier
	s_setprio 1
	v_mfma_f32_16x16x32_bf16 v[128:131], v[144:147], v[180:183], v[128:131]
	v_mfma_f32_16x16x32_bf16 v[120:123], v[152:155], v[180:183], v[120:123]
	v_mfma_f32_16x16x32_bf16 v[112:115], v[144:147], v[188:191], v[112:115]
	v_mfma_f32_16x16x32_bf16 v[104:107], v[152:155], v[188:191], v[104:107]
	v_mfma_f32_16x16x32_bf16 v[96:99], v[144:147], v[202:205], v[96:99]
	v_mfma_f32_16x16x32_bf16 v[88:91], v[152:155], v[202:205], v[88:91]
	v_mfma_f32_16x16x32_bf16 v[80:83], v[144:147], v[210:213], v[80:83]
	v_mfma_f32_16x16x32_bf16 v[72:75], v[152:155], v[210:213], v[72:75]
	v_mfma_f32_16x16x32_bf16 v[128:131], v[148:151], v[184:187], v[128:131]
	v_mfma_f32_16x16x32_bf16 v[120:123], v[156:159], v[184:187], v[120:123]
	v_mfma_f32_16x16x32_bf16 v[112:115], v[148:151], v[192:195], v[112:115]
	v_mfma_f32_16x16x32_bf16 v[104:107], v[156:159], v[192:195], v[104:107]
	v_mfma_f32_16x16x32_bf16 v[96:99], v[148:151], v[206:209], v[96:99]
	v_mfma_f32_16x16x32_bf16 v[88:91], v[156:159], v[206:209], v[88:91]
	v_mfma_f32_16x16x32_bf16 v[80:83], v[148:151], v[214:217], v[80:83]
	v_mfma_f32_16x16x32_bf16 v[72:75], v[156:159], v[214:217], v[72:75]
	s_setprio 0
	s_setprio 1
	v_mfma_f32_16x16x32_bf16 v[124:127], v[160:163], v[180:183], v[124:127]
	v_mfma_f32_16x16x32_bf16 v[116:119], v[172:175], v[180:183], v[116:119]
	v_mfma_f32_16x16x32_bf16 v[108:111], v[160:163], v[188:191], v[108:111]
	v_mfma_f32_16x16x32_bf16 v[100:103], v[172:175], v[188:191], v[100:103]
	v_mfma_f32_16x16x32_bf16 v[92:95], v[160:163], v[202:205], v[92:95]
	v_mfma_f32_16x16x32_bf16 v[84:87], v[172:175], v[202:205], v[84:87]
	v_mfma_f32_16x16x32_bf16 v[76:79], v[160:163], v[210:213], v[76:79]
	v_mfma_f32_16x16x32_bf16 v[68:71], v[172:175], v[210:213], v[68:71]
	v_mfma_f32_16x16x32_bf16 v[124:127], v[168:171], v[184:187], v[124:127]
	v_mfma_f32_16x16x32_bf16 v[116:119], v[176:179], v[184:187], v[116:119]
	v_mfma_f32_16x16x32_bf16 v[108:111], v[168:171], v[192:195], v[108:111]
	v_mfma_f32_16x16x32_bf16 v[100:103], v[176:179], v[192:195], v[100:103]
	v_mfma_f32_16x16x32_bf16 v[92:95], v[168:171], v[206:209], v[92:95]
	v_mfma_f32_16x16x32_bf16 v[84:87], v[176:179], v[206:209], v[84:87]
	v_mfma_f32_16x16x32_bf16 v[76:79], v[168:171], v[214:217], v[76:79]
	v_mfma_f32_16x16x32_bf16 v[68:71], v[176:179], v[214:217], v[68:71]
	s_setprio 0
	s_barrier
; #define PG8_STAGE(bufoff, gbase, voff) do { _Pragma("unroll") for (int _i = 0; _i < 2; ++_i) \
;         __builtin_amdgcn_global_load_lds((const unsigned*)((const char*)(gbase) + (voff)[_i]), (PG8_LAS unsigned*)(lds + (bufoff) + ldsw + _i * 8192), 16, 0, 0); } while (0)
; #define PG8_LDA(dst, b, h) do { _Pragma("unroll") for (int m = 0; m < 4; ++m) _Pragma("unroll") for (int k = 0; k < 2; ++k) dst[m][k] = *(const PG8_LAS bf16x8*)(lds + PG8_SA(b, h) + aoff + m * 2048 + k * 1024); } while (0)
; #define PG8_MMA(ai, bj, At, Bt) do { __builtin_amdgcn_s_setprio(1); _Pragma("unroll") for (int m = 0; m < 4; ++m) _Pragma("unroll") for (int n = 0; n < 2; ++n) _Pragma("unroll") for (int k = 0; k < 2; ++k) \
;         acc[ai][bj][m][n] = __builtin_amdgcn_mfma_f32_16x16x32_bf16(Bt[n][k], At[m][k], acc[ai][bj][m][n], 0, 0, 0); __builtin_amdgcn_s_setprio(0); } while (0)
; #define PG8_WAIT_V(n) asm volatile("s_waitcnt vmcnt(" #n ")" ::: "memory")
; #define PG8_WAIT_L(n) asm volatile("s_waitcnt lgkmcnt(" #n ")" ::: "memory")
; #define PG8_BAR __builtin_amdgcn_s_barrier()
; #define PG8_SCHED __builtin_amdgcn_sched_barrier(0)
; template <class Epi, class Sched, bool ALIGN_EPI = false, bool SP2 = false>
; __device__ __forceinline__ void gemm_phase(PG8_LAS unsigned char* lds, const Gemm g, const Sched& S, const Epi& E) {
;     ...
;         for (int t = 0; t < nt; t += 2) {
;             const bool last = (t == nt - 2);
;             const char* a1 = cA + (size_t)(t + 1) * kstep;
;             const char* a2 = last ? nA : cA + (size_t)(t + 2) * kstep; const char* b2 = last ? nB : cB + (size_t)(t + 2) * kstep;
;             const char* a3 = a2 + kstep; const char* b3 = b2 + kstep;
;             if (last && has_next) S.a_ready(nxt);
;     ...
;             PG8_LDA(At, 1, 1); PG8_STAGE(PG8_SB(1, 0), b3, voffB); PG8_STAGE(PG8_SB(1, 1), b3 + hstep, voffB); PG8_STAGE(PG8_SA(1, 0), a3, voffA);
;             PG8_WAIT_V(8); PG8_WAIT_L(0); PG8_BAR; PG8_MMA(1, 0, At, B0); PG8_MMA(1, 1, At, B1); PG8_BAR; PG8_SCHED;
	s_add_i32 s26, s47, s35
	s_add_i32 m0, s26, 0xffffff80
	ds_read_b128 v[180:183], v166 offset:49152
	ds_read_b128 v[184:187], v166 offset:50176
	ds_read_b128 v[188:191], v166 offset:51200
	ds_read_b128 v[192:195], v166 offset:52224
	ds_read_b128 v[202:205], v166 offset:53248
	ds_read_b128 v[206:209], v166 offset:54272
	ds_read_b128 v[210:213], v166 offset:55296
	ds_read_b128 v[214:217], v166 offset:56320
	global_load_lds_dwordx4 v[198:199], off offset:128
	s_add_i32 m0, s26, 0x1f80
	s_add_u32 s24, s24, 0x40080
	s_addc_u32 s25, s25, 0
	s_add_i32 s26, s48, s35
	global_load_lds_dwordx4 v[218:219], off offset:128
	s_mov_b32 m0, s26
	v_lshl_add_u64 v[198:199], s[24:25], 0, v[134:135]
	global_load_lds_dwordx4 v[198:199], off
	s_add_i32 m0, s26, 0x2000
	v_lshl_add_u64 v[198:199], s[24:25], 0, v[0:1]
	global_load_lds_dwordx4 v[198:199], off
	s_add_i32 m0, s41, 0xffffff80
	s_add_u32 s8, s8, 0x100
	s_addc_u32 s9, s9, 0
	global_load_lds_dwordx4 v[220:221], off offset:128
	s_add_i32 m0, s42, 0xffffff80
	s_add_u32 s44, s44, 0x100
	s_addc_u32 s45, s45, 0
	global_load_lds_dwordx4 v[222:223], off offset:128
	s_waitcnt vmcnt(8) lgkmcnt(0)
	s_barrier
	s_setprio 1
	v_mfma_f32_16x16x32_bf16 v[64:67], v[144:147], v[180:183], v[64:67]
	v_mfma_f32_16x16x32_bf16 v[56:59], v[152:155], v[180:183], v[56:59]
	v_mfma_f32_16x16x32_bf16 v[48:51], v[144:147], v[188:191], v[48:51]
	v_mfma_f32_16x16x32_bf16 v[40:43], v[152:155], v[188:191], v[40:43]
	v_mfma_f32_16x16x32_bf16 v[32:35], v[144:147], v[202:205], v[32:35]
	v_mfma_f32_16x16x32_bf16 v[24:27], v[152:155], v[202:205], v[24:27]
	v_mfma_f32_16x16x32_bf16 v[16:19], v[144:147], v[210:213], v[16:19]
	v_mfma_f32_16x16x32_bf16 v[8:11], v[152:155], v[210:213], v[8:11]
	v_mfma_f32_16x16x32_bf16 v[64:67], v[148:151], v[184:187], v[64:67]
	v_mfma_f32_16x16x32_bf16 v[56:59], v[156:159], v[184:187], v[56:59]
	v_mfma_f32_16x16x32_bf16 v[48:51], v[148:151], v[192:195], v[48:51]
	v_mfma_f32_16x16x32_bf16 v[40:43], v[156:159], v[192:195], v[40:43]
	v_mfma_f32_16x16x32_bf16 v[32:35], v[148:151], v[206:209], v[32:35]
	v_mfma_f32_16x16x32_bf16 v[24:27], v[156:159], v[206:209], v[24:27]
	v_mfma_f32_16x16x32_bf16 v[16:19], v[148:151], v[214:217], v[16:19]
	v_mfma_f32_16x16x32_bf16 v[8:11], v[156:159], v[214:217], v[8:11]
	s_setprio 0
	s_setprio 1
	v_mfma_f32_16x16x32_bf16 v[60:63], v[160:163], v[180:183], v[60:63]
	v_mfma_f32_16x16x32_bf16 v[52:55], v[172:175], v[180:183], v[52:55]
	v_mfma_f32_16x16x32_bf16 v[44:47], v[160:163], v[188:191], v[44:47]
	v_mfma_f32_16x16x32_bf16 v[36:39], v[172:175], v[188:191], v[36:39]
	v_mfma_f32_16x16x32_bf16 v[28:31], v[160:163], v[202:205], v[28:31]
	v_mfma_f32_16x16x32_bf16 v[20:23], v[172:175], v[202:205], v[20:23]
	v_mfma_f32_16x16x32_bf16 v[12:15], v[160:163], v[210:213], v[12:15]
	v_mfma_f32_16x16x32_bf16 v[4:7], v[172:175], v[210:213], v[4:7]
	v_mfma_f32_16x16x32_bf16 v[60:63], v[168:171], v[184:187], v[60:63]
	v_mfma_f32_16x16x32_bf16 v[52:55], v[176:179], v[184:187], v[52:55]
	v_mfma_f32_16x16x32_bf16 v[44:47], v[168:171], v[192:195], v[44:47]
	v_mfma_f32_16x16x32_bf16 v[36:39], v[176:179], v[192:195], v[36:39]
	v_mfma_f32_16x16x32_bf16 v[28:31], v[168:171], v[206:209], v[28:31]
	v_mfma_f32_16x16x32_bf16 v[20:23], v[176:179], v[206:209], v[20:23]
	v_mfma_f32_16x16x32_bf16 v[12:15], v[168:171], v[214:217], v[12:15]
	v_mfma_f32_16x16x32_bf16 v[4:7], v[176:179], v[214:217], v[4:7]
	s_setprio 0
	s_barrier
	s_add_i32 s46, s46, 2
	s_cmp_gt_u32 s46, 13
	s_cbranch_scc0 .LBB0_405
	s_and_b64 vcc, exec, s[14:15]
	s_cbranch_vccz .LBB0_408
	s_barrier

; __device__ __forceinline__ int opaque_tid() { int t = (int)threadIdx.x; asm volatile("" : "+v"(t)); return t; }
; #define PG8_STAGE(bufoff, gbase, voff) do { _Pragma("unroll") for (int _i = 0; _i < 2; ++_i) \
;         __builtin_amdgcn_global_load_lds((const unsigned*)((const char*)(gbase) + (voff)[_i]), (PG8_LAS unsigned*)(lds + (bufoff) + ldsw + _i * 8192), 16, 0, 0); } while (0)
; #define PG8_WAIT_V(n) asm volatile("s_waitcnt vmcnt(" #n ")" ::: "memory")
; #define PG8_BAR __builtin_amdgcn_s_barrier()
; template <class Epi, class Sched, bool ALIGN_EPI = false, bool SP2 = false>
; __device__ __forceinline__ void gemm_phase(PG8_LAS unsigned char* lds, const Gemm g, const Sched& S, const Epi& E) {
;     const int tid = opaque_tid(), wid = __builtin_amdgcn_readfirstlane(tid >> 6), lane = tid & 63, wr = wid >> 2, wc = wid & 3, fr = lane & 15, fq = lane >> 4;
;     const int K = g.K, nt = K / BK;
;     unsigned voffA[2], voffB[2];
; #pragma unroll
;     for (int i = 0; i < 2; ++i) { int R, C; stage_rc(tid * 16 + i * 8192, R, C); const int Rb = Epi::PERM ? ((R & ~31) + perm32(R & 31)) : R;
;         voffA[i] = (unsigned)(R * K + C) * 2u; voffB[i] = (unsigned)(Rb * K + C) * 2u; }
;     const size_t kstep = (size_t)(BK * 2);
;     const size_t hstep = (size_t)HALF * K * 2;
;     const size_t tstep = 2 * hstep;
;     const unsigned ldsw = (unsigned)wid * 1024u;
;     const int aoff = lds_byte(wr * 64 + fr, fq * 8), boff = lds_byte(wc * 32 + fr, fq * 8);
;     ...
;         PG8_STAGE(PG8_SB(0, 0), cB, voffB); PG8_STAGE(PG8_SB(0, 1), cB + hstep, voffB); PG8_STAGE(PG8_SA(0, 0), cA, voffA); PG8_STAGE(PG8_SA(0, 1), cA + hstep, voffA);
;         if (wr == 1) PG8_BAR;
;         PG8_WAIT_V(2); PG8_BAR;
;         PG8_STAGE(PG8_SB(1, 0), cB + kstep, voffB); PG8_STAGE(PG8_SA(1, 0), cA + kstep, voffA); PG8_STAGE(PG8_SB(1, 1), cB + hstep + kstep, voffB);
;         PG8_WAIT_V(6); PG8_BAR;
.LBB0_466:
	s_add_u32 s18, s14, 0x6400000
	s_addc_u32 s19, s15, 0
	s_add_u32 s14, s14, 0x1a400000
	s_addc_u32 s15, s15, 0
	s_and_b32 s46, s5, 3
	s_add_i32 m0, s40, 0x18000
	v_lshl_add_u64 v[10:11], v[10:11], 0, s[82:83]
	s_lshl_b32 s5, s4, 13
	s_lshl_b32 s9, s46, 12
	s_waitcnt vmcnt(2)
	s_barrier
	global_load_lds_dwordx4 v[10:11], off
	v_lshl_add_u64 v[8:9], v[8:9], 0, s[82:83]
	s_add_i32 m0, s40, 0x1a000
	s_add_i32 s47, s40, 0x8000
	s_add_i32 s48, s40, 0xa000
	global_load_lds_dwordx4 v[8:9], off
	v_lshl_add_u64 v[4:5], v[4:5], 0, s[82:83]
	s_mov_b32 m0, s47
	s_add_u32 s6, s28, 0xb0080
	global_load_lds_dwordx4 v[4:5], off
	v_lshl_add_u64 v[4:5], v[6:7], 0, s[82:83]
	s_mov_b32 m0, s48
	s_addc_u32 s7, s29, 0
	global_load_lds_dwordx4 v[4:5], off
	s_add_i32 m0, s40, 0x1c000
	v_lshl_add_u64 v[4:5], s[6:7], 0, v[192:193]
	global_load_lds_dwordx4 v[4:5], off
	v_lshl_add_u64 v[4:5], s[6:7], 0, v[202:203]
	s_add_i32 m0, s40, 0x1e000
	s_mov_b32 s1, 0xb000
	global_load_lds_dwordx4 v[4:5], off
	v_bfe_u32 v4, v12, 4, 2
	v_and_b32_e32 v5, 15, v12
	v_lshlrev_b32_e32 v7, 4, v4
	v_lshl_or_b32 v3, s4, 6, v5
	v_lshl_or_b32 v5, v5, 6, v7
	v_lshlrev_b32_e32 v7, 2, v12
	v_and_b32_e32 v7, 32, v7
	v_lshlrev_b32_e32 v6, 3, v4
	v_bitop3_b32 v8, v5, s5, v7 bitop3:0xde
	v_bitop3_b32 v234, v5, s9, v7 bitop3:0xde
	v_add_u32_e32 v234, 0x10000, v234
	v_cmp_eq_u32_e64 s[4:5], 0, v4
	v_lshrrev_b32_e32 v5, 1, v13
	v_mul_lo_u32 v4, v15, s77
	v_mad_u64_u32 v[4:5], s[6:7], v5, s1, v[4:5]
	v_or_b32_e32 v4, v4, v14
	s_cmpk_lt_u32 s8, 0x100
	v_add_lshl_u32 v4, v4, v16, 1
	v_mov_b32_e32 v5, v2
	s_mov_b64 s[8:9], 0xb0080
	v_lshl_add_u64 v[204:205], v[4:5], 0, s[8:9]
	v_lshrrev_b32_e32 v5, 1, v17
	v_mul_lo_u32 v4, v19, s77
	v_mad_u64_u32 v[4:5], s[6:7], v5, s1, v[4:5]
	s_waitcnt vmcnt(6)
	v_or_b32_e32 v4, v4, v18
	v_add_lshl_u32 v4, v4, v20, 1
	v_mov_b32_e32 v5, v2
	v_lshl_or_b32 v235, s46, 5, v6
	s_cselect_b64 s[20:21], -1, 0
	s_mov_b32 s72, 0
	s_ashr_i32 s49, s34, 31
	v_lshl_add_u64 v[206:207], v[4:5], 0, s[8:9]
	v_add_u32_e32 v236, 0, v8
	s_barrier
	s_branch .LBB0_469

; #define PG8_STAGE(bufoff, gbase, voff) do { _Pragma("unroll") for (int _i = 0; _i < 2; ++_i) \
;         __builtin_amdgcn_global_load_lds((const unsigned*)((const char*)(gbase) + (voff)[_i]), (PG8_LAS unsigned*)(lds + (bufoff) + ldsw + _i * 8192), 16, 0, 0); } while (0)
; #define PG8_LDA(dst, b, h) do { _Pragma("unroll") for (int m = 0; m < 4; ++m) _Pragma("unroll") for (int k = 0; k < 2; ++k) dst[m][k] = *(const PG8_LAS bf16x8*)(lds + PG8_SA(b, h) + aoff + m * 2048 + k * 1024); } while (0)
; #define PG8_LDB(dst, b, h) do { _Pragma("unroll") for (int n = 0; n < 2; ++n) _Pragma("unroll") for (int k = 0; k < 2; ++k) dst[n][k] = *(const PG8_LAS bf16x8*)(lds + PG8_SB(b, h) + boff + n * 2048 + k * 1024); } while (0)
; #define PG8_MMA(ai, bj, At, Bt) do { __builtin_amdgcn_s_setprio(1); _Pragma("unroll") for (int m = 0; m < 4; ++m) _Pragma("unroll") for (int n = 0; n < 2; ++n) _Pragma("unroll") for (int k = 0; k < 2; ++k) \
;         acc[ai][bj][m][n] = __builtin_amdgcn_mfma_f32_16x16x32_bf16(Bt[n][k], At[m][k], acc[ai][bj][m][n], 0, 0, 0); __builtin_amdgcn_s_setprio(0); } while (0)
; #define PG8_WAIT_V(n) asm volatile("s_waitcnt vmcnt(" #n ")" ::: "memory")
; #define PG8_WAIT_L(n) asm volatile("s_waitcnt lgkmcnt(" #n ")" ::: "memory")
; #define PG8_BAR __builtin_amdgcn_s_barrier()
; template <class Epi, class Sched, bool ALIGN_EPI = false, bool SP2 = false>
; __device__ __forceinline__ void gemm_phase(PG8_LAS unsigned char* lds, const Gemm g, const Sched& S, const Epi& E) {
;     ...
;             const char* a1 = cA + (size_t)(t + 1) * kstep;
;             const char* a2 = last ? nA : cA + (size_t)(t + 2) * kstep; const char* b2 = last ? nB : cB + (size_t)(t + 2) * kstep;
;             const char* a3 = a2 + kstep; const char* b3 = b2 + kstep;
;             if (last && has_next) S.a_ready(nxt);
;             if constexpr (SP2) {
;             PG8_LDB(B0, 0, 0); PG8_LDB(B1, 0, 1); PG8_SCHED; PG8_LDA(At, 0, 0); PG8_STAGE(PG8_SA(1, 1), a1 + hstep, voffA);
;             PG8_WAIT_V(8); PG8_WAIT_L(0); PG8_BAR; PG8_MMA(0, 0, At, B0); PG8_MMA(0, 1, At, B1); PG8_BAR; PG8_SCHED;
;             PG8_LDA(At, 0, 1); PG8_STAGE(PG8_SB(0, 0), b2, voffB); PG8_STAGE(PG8_SB(0, 1), b2 + hstep, voffB); PG8_STAGE(PG8_SA(0, 0), a2, voffA);
;             PG8_WAIT_V(8); PG8_WAIT_L(0); PG8_BAR; PG8_MMA(1, 0, At, B0); PG8_MMA(1, 1, At, B1); PG8_BAR; PG8_SCHED;
.LBB0_480:
	s_add_u32 s8, s26, 0x100
	s_addc_u32 s9, s27, 0
	s_add_i32 s54, 0, 0x10000
	s_cmp_eq_u32 s53, 40
	s_cselect_b32 s31, s23, s9
	s_cselect_b32 s30, s22, s8
	s_cselect_b32 s29, s25, s45
	s_cselect_b32 s28, s24, s44
	s_add_i32 s55, 0, 0x14000
	ds_read_b128 v[68:71], v234
	ds_read_b128 v[80:83], v234 offset:1024
	ds_read_b128 v[92:95], v234 offset:2048
	ds_read_b128 v[100:103], v234 offset:3072
	ds_read_b128 v[112:115], v234 offset:16384
	ds_read_b128 v[120:123], v234 offset:17408
	ds_read_b128 v[132:135], v234 offset:18432
	ds_read_b128 v[144:147], v234 offset:19456
	v_lshl_add_u64 v[198:199], s[26:27], 0, v[204:205]
	s_add_i32 m0, s40, 0xc000
	ds_read_b128 v[156:159], v236
	ds_read_b128 v[168:171], v236 offset:1024
	ds_read_b128 v[172:175], v236 offset:2048
	ds_read_b128 v[176:179], v236 offset:3072
	ds_read_b128 v[180:183], v236 offset:4096
	ds_read_b128 v[184:187], v236 offset:5120
	ds_read_b128 v[188:191], v236 offset:6144
	ds_read_b128 v[208:211], v236 offset:7168
	global_load_lds_dwordx4 v[198:199], off
	s_add_i32 m0, s40, 0xe000
	v_lshl_add_u64 v[198:199], s[26:27], 0, v[206:207]
	global_load_lds_dwordx4 v[198:199], off
	s_waitcnt vmcnt(8) lgkmcnt(0)
	s_barrier
	s_setprio 1
	v_mfma_f32_16x16x32_bf16 v[164:167], v[68:71], v[156:159], v[164:167]
	v_mfma_f32_16x16x32_bf16 v[160:163], v[92:95], v[156:159], v[160:163]
	v_mfma_f32_16x16x32_bf16 v[140:143], v[68:71], v[172:175], v[140:143]
	v_mfma_f32_16x16x32_bf16 v[136:139], v[92:95], v[172:175], v[136:139]
	v_mfma_f32_16x16x32_bf16 v[116:119], v[68:71], v[180:183], v[116:119]
	v_mfma_f32_16x16x32_bf16 v[108:111], v[92:95], v[180:183], v[108:111]
	v_mfma_f32_16x16x32_bf16 v[88:91], v[68:71], v[188:191], v[88:91]
	v_mfma_f32_16x16x32_bf16 v[84:87], v[92:95], v[188:191], v[84:87]
	v_mfma_f32_16x16x32_bf16 v[164:167], v[80:83], v[168:171], v[164:167]
	v_mfma_f32_16x16x32_bf16 v[160:163], v[100:103], v[168:171], v[160:163]
	v_mfma_f32_16x16x32_bf16 v[140:143], v[80:83], v[176:179], v[140:143]
	v_mfma_f32_16x16x32_bf16 v[136:139], v[100:103], v[176:179], v[136:139]
	v_mfma_f32_16x16x32_bf16 v[116:119], v[80:83], v[184:187], v[116:119]
	v_mfma_f32_16x16x32_bf16 v[108:111], v[100:103], v[184:187], v[108:111]
	v_mfma_f32_16x16x32_bf16 v[88:91], v[80:83], v[208:211], v[88:91]
	v_mfma_f32_16x16x32_bf16 v[84:87], v[100:103], v[208:211], v[84:87]
	s_setprio 0
	s_setprio 1
	v_mfma_f32_16x16x32_bf16 v[152:155], v[112:115], v[156:159], v[152:155]
	v_mfma_f32_16x16x32_bf16 v[148:151], v[132:135], v[156:159], v[148:151]
	v_mfma_f32_16x16x32_bf16 v[128:131], v[112:115], v[172:175], v[128:131]
	v_mfma_f32_16x16x32_bf16 v[124:127], v[132:135], v[172:175], v[124:127]
	v_mfma_f32_16x16x32_bf16 v[104:107], v[112:115], v[180:183], v[104:107]
	v_mfma_f32_16x16x32_bf16 v[96:99], v[132:135], v[180:183], v[96:99]
	v_mfma_f32_16x16x32_bf16 v[76:79], v[112:115], v[188:191], v[76:79]
	v_mfma_f32_16x16x32_bf16 v[72:75], v[132:135], v[188:191], v[72:75]
	v_mfma_f32_16x16x32_bf16 v[152:155], v[120:123], v[168:171], v[152:155]
	v_mfma_f32_16x16x32_bf16 v[148:151], v[144:147], v[168:171], v[148:151]
	v_mfma_f32_16x16x32_bf16 v[128:131], v[120:123], v[176:179], v[128:131]
	v_mfma_f32_16x16x32_bf16 v[124:127], v[144:147], v[176:179], v[124:127]
	v_mfma_f32_16x16x32_bf16 v[104:107], v[120:123], v[184:187], v[104:107]
	v_mfma_f32_16x16x32_bf16 v[96:99], v[144:147], v[184:187], v[96:99]
	v_mfma_f32_16x16x32_bf16 v[76:79], v[120:123], v[208:211], v[76:79]
	v_mfma_f32_16x16x32_bf16 v[72:75], v[144:147], v[208:211], v[72:75]
	s_setprio 0
	s_barrier
	s_add_i32 s26, s54, s39
	v_lshl_add_u64 v[198:199], s[28:29], 0, v[192:193]
	s_mov_b32 m0, s26
	ds_read_b128 v[156:159], v236 offset:16384
	ds_read_b128 v[168:171], v236 offset:17408
	ds_read_b128 v[172:175], v236 offset:18432
	ds_read_b128 v[176:179], v236 offset:19456
	ds_read_b128 v[180:183], v236 offset:20480
	ds_read_b128 v[184:187], v236 offset:21504
	ds_read_b128 v[188:191], v236 offset:22528
	ds_read_b128 v[208:211], v236 offset:23552
	global_load_lds_dwordx4 v[198:199], off
	s_add_i32 m0, s26, 0x2000
	s_add_u32 s26, s28, 0xb0000
	v_lshl_add_u64 v[212:213], s[28:29], 0, v[202:203]
	s_addc_u32 s27, s29, 0
	s_add_i32 s54, s55, s39
	global_load_lds_dwordx4 v[212:213], off
	v_lshl_add_u64 v[214:215], s[26:27], 0, v[192:193]
	s_mov_b32 m0, s54
	v_lshl_add_u64 v[216:217], s[30:31], 0, v[194:195]
	global_load_lds_dwordx4 v[214:215], off
	s_add_i32 m0, s54, 0x2000
	v_lshl_add_u64 v[214:215], s[26:27], 0, v[202:203]
	global_load_lds_dwordx4 v[214:215], off
	s_mov_b32 m0, s40
	v_lshl_add_u64 v[214:215], s[30:31], 0, v[0:1]
	global_load_lds_dwordx4 v[214:215], off
	s_mov_b32 m0, s41
	s_add_i32 s54, 0, 0x18000
	global_load_lds_dwordx4 v[216:217], off
	s_waitcnt vmcnt(8) lgkmcnt(0)
	s_barrier
; #define PG8_STAGE(bufoff, gbase, voff) do { _Pragma("unroll") for (int _i = 0; _i < 2; ++_i) \
;         __builtin_amdgcn_global_load_lds((const unsigned*)((const char*)(gbase) + (voff)[_i]), (PG8_LAS unsigned*)(lds + (bufoff) + ldsw + _i * 8192), 16, 0, 0); } while (0)
; #define PG8_LDA(dst, b, h) do { _Pragma("unroll") for (int m = 0; m < 4; ++m) _Pragma("unroll") for (int k = 0; k < 2; ++k) dst[m][k] = *(const PG8_LAS bf16x8*)(lds + PG8_SA(b, h) + aoff + m * 2048 + k * 1024); } while (0)
; #define PG8_LDB(dst, b, h) do { _Pragma("unroll") for (int n = 0; n < 2; ++n) _Pragma("unroll") for (int k = 0; k < 2; ++k) dst[n][k] = *(const PG8_LAS bf16x8*)(lds + PG8_SB(b, h) + boff + n * 2048 + k * 1024); } while (0)
; #define PG8_MMA(ai, bj, At, Bt) do { __builtin_amdgcn_s_setprio(1); _Pragma("unroll") for (int m = 0; m < 4; ++m) _Pragma("unroll") for (int n = 0; n < 2; ++n) _Pragma("unroll") for (int k = 0; k < 2; ++k) \
;         acc[ai][bj][m][n] = __builtin_amdgcn_mfma_f32_16x16x32_bf16(Bt[n][k], At[m][k], acc[ai][bj][m][n], 0, 0, 0); __builtin_amdgcn_s_setprio(0); } while (0)
; #define PG8_WAIT_V(n) asm volatile("s_waitcnt vmcnt(" #n ")" ::: "memory")
; #define PG8_WAIT_L(n) asm volatile("s_waitcnt lgkmcnt(" #n ")" ::: "memory")
; #define PG8_BAR __builtin_amdgcn_s_barrier()
; #define PG8_SCHED __builtin_amdgcn_sched_barrier(0)
; template <class Epi, class Sched, bool ALIGN_EPI = false, bool SP2 = false>
; __device__ __forceinline__ void gemm_phase(PG8_LAS unsigned char* lds, const Gemm g, const Sched& S, const Epi& E) {
;     ...
;             PG8_WAIT_V(8); PG8_WAIT_L(0); PG8_BAR; PG8_MMA(1, 0, At, B0); PG8_MMA(1, 1, At, B1); PG8_BAR; PG8_SCHED;
;             PG8_LDB(B0, 1, 0); PG8_LDB(B1, 1, 1); PG8_SCHED; PG8_LDA(At, 1, 0); PG8_STAGE(PG8_SA(0, 1), a2 + hstep, voffA);
;             PG8_WAIT_V(8); PG8_WAIT_L(0); PG8_BAR; PG8_MMA(0, 0, At, B0); PG8_MMA(0, 1, At, B1); PG8_BAR; PG8_SCHED;
	s_setprio 1
	v_mfma_f32_16x16x32_bf16 v[64:67], v[68:71], v[156:159], v[64:67]
	v_mfma_f32_16x16x32_bf16 v[60:63], v[92:95], v[156:159], v[60:63]
	v_mfma_f32_16x16x32_bf16 v[48:51], v[68:71], v[172:175], v[48:51]
	v_mfma_f32_16x16x32_bf16 v[44:47], v[92:95], v[172:175], v[44:47]
	v_mfma_f32_16x16x32_bf16 v[32:35], v[68:71], v[180:183], v[32:35]
	v_mfma_f32_16x16x32_bf16 v[28:31], v[92:95], v[180:183], v[28:31]
	v_mfma_f32_16x16x32_bf16 v[16:19], v[68:71], v[188:191], v[16:19]
	v_mfma_f32_16x16x32_bf16 v[12:15], v[92:95], v[188:191], v[12:15]
	v_mfma_f32_16x16x32_bf16 v[64:67], v[80:83], v[168:171], v[64:67]
	v_mfma_f32_16x16x32_bf16 v[60:63], v[100:103], v[168:171], v[60:63]
	v_mfma_f32_16x16x32_bf16 v[48:51], v[80:83], v[176:179], v[48:51]
	v_mfma_f32_16x16x32_bf16 v[44:47], v[100:103], v[176:179], v[44:47]
	v_mfma_f32_16x16x32_bf16 v[32:35], v[80:83], v[184:187], v[32:35]
	v_mfma_f32_16x16x32_bf16 v[28:31], v[100:103], v[184:187], v[28:31]
	v_mfma_f32_16x16x32_bf16 v[16:19], v[80:83], v[208:211], v[16:19]
	v_mfma_f32_16x16x32_bf16 v[12:15], v[100:103], v[208:211], v[12:15]
	s_setprio 0
	s_setprio 1
	v_mfma_f32_16x16x32_bf16 v[56:59], v[112:115], v[156:159], v[56:59]
	v_mfma_f32_16x16x32_bf16 v[52:55], v[132:135], v[156:159], v[52:55]
	v_mfma_f32_16x16x32_bf16 v[40:43], v[112:115], v[172:175], v[40:43]
	v_mfma_f32_16x16x32_bf16 v[36:39], v[132:135], v[172:175], v[36:39]
	v_mfma_f32_16x16x32_bf16 v[24:27], v[112:115], v[180:183], v[24:27]
	v_mfma_f32_16x16x32_bf16 v[20:23], v[132:135], v[180:183], v[20:23]
	v_mfma_f32_16x16x32_bf16 v[8:11], v[112:115], v[188:191], v[8:11]
	v_mfma_f32_16x16x32_bf16 v[4:7], v[132:135], v[188:191], v[4:7]
	v_mfma_f32_16x16x32_bf16 v[56:59], v[120:123], v[168:171], v[56:59]
	v_mfma_f32_16x16x32_bf16 v[52:55], v[144:147], v[168:171], v[52:55]
	v_mfma_f32_16x16x32_bf16 v[40:43], v[120:123], v[176:179], v[40:43]
	v_mfma_f32_16x16x32_bf16 v[36:39], v[144:147], v[176:179], v[36:39]
	v_mfma_f32_16x16x32_bf16 v[24:27], v[120:123], v[184:187], v[24:27]
	v_mfma_f32_16x16x32_bf16 v[20:23], v[144:147], v[184:187], v[20:23]
	v_mfma_f32_16x16x32_bf16 v[8:11], v[120:123], v[208:211], v[8:11]
	v_mfma_f32_16x16x32_bf16 v[4:7], v[144:147], v[208:211], v[4:7]
	s_setprio 0
	s_barrier
	s_add_i32 s55, 0, 0x1c000
	ds_read_b128 v[68:71], v234 offset:32768
	ds_read_b128 v[80:83], v234 offset:33792
	ds_read_b128 v[92:95], v234 offset:34816
	ds_read_b128 v[100:103], v234 offset:35840
	ds_read_b128 v[112:115], v234 offset:49152
	ds_read_b128 v[120:123], v234 offset:50176
	ds_read_b128 v[132:135], v234 offset:51200
	ds_read_b128 v[144:147], v234 offset:52224
	s_add_u32 s26, s30, 0xb0000
	s_addc_u32 s27, s31, 0
	s_mov_b32 m0, s42
	v_lshl_add_u64 v[218:219], s[26:27], 0, v[0:1]
	ds_read_b128 v[156:159], v236 offset:32768
	ds_read_b128 v[168:171], v236 offset:33792
	ds_read_b128 v[172:175], v236 offset:34816
	ds_read_b128 v[176:179], v236 offset:35840
	ds_read_b128 v[180:183], v236 offset:36864
	ds_read_b128 v[184:187], v236 offset:37888
	ds_read_b128 v[188:191], v236 offset:38912
	ds_read_b128 v[208:211], v236 offset:39936
	global_load_lds_dwordx4 v[218:219], off
	s_mov_b32 m0, s43
	v_lshl_add_u64 v[218:219], s[26:27], 0, v[194:195]
	global_load_lds_dwordx4 v[218:219], off
	s_waitcnt vmcnt(8) lgkmcnt(0)
	s_barrier
	s_setprio 1
	v_mfma_f32_16x16x32_bf16 v[164:167], v[68:71], v[156:159], v[164:167]
	v_mfma_f32_16x16x32_bf16 v[160:163], v[92:95], v[156:159], v[160:163]
	v_mfma_f32_16x16x32_bf16 v[140:143], v[68:71], v[172:175], v[140:143]
	v_mfma_f32_16x16x32_bf16 v[136:139], v[92:95], v[172:175], v[136:139]
	v_mfma_f32_16x16x32_bf16 v[116:119], v[68:71], v[180:183], v[116:119]
	v_mfma_f32_16x16x32_bf16 v[108:111], v[92:95], v[180:183], v[108:111]
	v_mfma_f32_16x16x32_bf16 v[88:91], v[68:71], v[188:191], v[88:91]
	v_mfma_f32_16x16x32_bf16 v[84:87], v[92:95], v[188:191], v[84:87]
	v_mfma_f32_16x16x32_bf16 v[164:167], v[80:83], v[168:171], v[164:167]
	v_mfma_f32_16x16x32_bf16 v[160:163], v[100:103], v[168:171], v[160:163]
	v_mfma_f32_16x16x32_bf16 v[140:143], v[80:83], v[176:179], v[140:143]
	v_mfma_f32_16x16x32_bf16 v[136:139], v[100:103], v[176:179], v[136:139]
	v_mfma_f32_16x16x32_bf16 v[116:119], v[80:83], v[184:187], v[116:119]
	v_mfma_f32_16x16x32_bf16 v[108:111], v[100:103], v[184:187], v[108:111]
	v_mfma_f32_16x16x32_bf16 v[88:91], v[80:83], v[208:211], v[88:91]
	v_mfma_f32_16x16x32_bf16 v[84:87], v[100:103], v[208:211], v[84:87]
	s_setprio 0
	s_setprio 1
	v_mfma_f32_16x16x32_bf16 v[152:155], v[112:115], v[156:159], v[152:155]
	v_mfma_f32_16x16x32_bf16 v[148:151], v[132:135], v[156:159], v[148:151]
	v_mfma_f32_16x16x32_bf16 v[128:131], v[112:115], v[172:175], v[128:131]
	v_mfma_f32_16x16x32_bf16 v[124:127], v[132:135], v[172:175], v[124:127]
	v_mfma_f32_16x16x32_bf16 v[104:107], v[112:115], v[180:183], v[104:107]
	v_mfma_f32_16x16x32_bf16 v[96:99], v[132:135], v[180:183], v[96:99]
	v_mfma_f32_16x16x32_bf16 v[76:79], v[112:115], v[188:191], v[76:79]
	v_mfma_f32_16x16x32_bf16 v[72:75], v[132:135], v[188:191], v[72:75]
	v_mfma_f32_16x16x32_bf16 v[152:155], v[120:123], v[168:171], v[152:155]
	v_mfma_f32_16x16x32_bf16 v[148:151], v[144:147], v[168:171], v[148:151]
	v_mfma_f32_16x16x32_bf16 v[128:131], v[120:123], v[176:179], v[128:131]
	v_mfma_f32_16x16x32_bf16 v[124:127], v[144:147], v[176:179], v[124:127]
	v_mfma_f32_16x16x32_bf16 v[104:107], v[120:123], v[184:187], v[104:107]
	v_mfma_f32_16x16x32_bf16 v[96:99], v[144:147], v[184:187], v[96:99]
	v_mfma_f32_16x16x32_bf16 v[76:79], v[120:123], v[208:211], v[76:79]
	v_mfma_f32_16x16x32_bf16 v[72:75], v[144:147], v[208:211], v[72:75]
	s_setprio 0
	s_barrier
; #define PG8_STAGE(bufoff, gbase, voff) do { _Pragma("unroll") for (int _i = 0; _i < 2; ++_i) \
;         __builtin_amdgcn_global_load_lds((const unsigned*)((const char*)(gbase) + (voff)[_i]), (PG8_LAS unsigned*)(lds + (bufoff) + ldsw + _i * 8192), 16, 0, 0); } while (0)
; #define PG8_LDA(dst, b, h) do { _Pragma("unroll") for (int m = 0; m < 4; ++m) _Pragma("unroll") for (int k = 0; k < 2; ++k) dst[m][k] = *(const PG8_LAS bf16x8*)(lds + PG8_SA(b, h) + aoff + m * 2048 + k * 1024); } while (0)
; #define PG8_MMA(ai, bj, At, Bt) do { __builtin_amdgcn_s_setprio(1); _Pragma("unroll") for (int m = 0; m < 4; ++m) _Pragma("unroll") for (int n = 0; n < 2; ++n) _Pragma("unroll") for (int k = 0; k < 2; ++k) \
;         acc[ai][bj][m][n] = __builtin_amdgcn_mfma_f32_16x16x32_bf16(Bt[n][k], At[m][k], acc[ai][bj][m][n], 0, 0, 0); __builtin_amdgcn_s_setprio(0); } while (0)
; #define PG8_WAIT_V(n) asm volatile("s_waitcnt vmcnt(" #n ")" ::: "memory")
; #define PG8_WAIT_L(n) asm volatile("s_waitcnt lgkmcnt(" #n ")" ::: "memory")
; #define PG8_BAR __builtin_amdgcn_s_barrier()
; #define PG8_SCHED __builtin_amdgcn_sched_barrier(0)
; template <class Epi, class Sched, bool ALIGN_EPI = false, bool SP2 = false>
; __device__ __forceinline__ void gemm_phase(PG8_LAS unsigned char* lds, const Gemm g, const Sched& S, const Epi& E) {
;     ...
;         for (int t = 0; t < nt; t += 2) {
;             const bool last = (t == nt - 2);
;             const char* a1 = cA + (size_t)(t + 1) * kstep;
;             const char* a2 = last ? nA : cA + (size_t)(t + 2) * kstep; const char* b2 = last ? nB : cB + (size_t)(t + 2) * kstep;
;             const char* a3 = a2 + kstep; const char* b3 = b2 + kstep;
;             if (last && has_next) S.a_ready(nxt);
;     ...
;             PG8_LDA(At, 1, 1); PG8_STAGE(PG8_SB(1, 0), b3, voffB); PG8_STAGE(PG8_SB(1, 1), b3 + hstep, voffB); PG8_STAGE(PG8_SA(1, 0), a3, voffA);
;             PG8_WAIT_V(8); PG8_WAIT_L(0); PG8_BAR; PG8_MMA(1, 0, At, B0); PG8_MMA(1, 1, At, B1); PG8_BAR; PG8_SCHED;
	s_add_i32 s26, s54, s39
	s_add_i32 m0, s26, 0xffffff80
	ds_read_b128 v[156:159], v236 offset:49152
	ds_read_b128 v[168:171], v236 offset:50176
	ds_read_b128 v[172:175], v236 offset:51200
	ds_read_b128 v[176:179], v236 offset:52224
	ds_read_b128 v[180:183], v236 offset:53248
	ds_read_b128 v[184:187], v236 offset:54272
	ds_read_b128 v[188:191], v236 offset:55296
	ds_read_b128 v[208:211], v236 offset:56320
	global_load_lds_dwordx4 v[198:199], off offset:128
	s_add_i32 m0, s26, 0x1f80
	s_add_u32 s26, s28, 0xb0080
	s_addc_u32 s27, s29, 0
	s_add_i32 s28, s55, s39
	global_load_lds_dwordx4 v[212:213], off offset:128
	s_mov_b32 m0, s28
	v_lshl_add_u64 v[198:199], s[26:27], 0, v[192:193]
	global_load_lds_dwordx4 v[198:199], off
	s_add_i32 m0, s28, 0x2000
	v_lshl_add_u64 v[198:199], s[26:27], 0, v[202:203]
	global_load_lds_dwordx4 v[198:199], off
	s_add_i32 m0, s47, 0xffffff80
	s_add_u32 s44, s44, 0x100
	s_addc_u32 s45, s45, 0
	global_load_lds_dwordx4 v[214:215], off offset:128
	s_add_i32 m0, s48, 0xffffff80
	s_mov_b64 s[26:27], s[8:9]
	global_load_lds_dwordx4 v[216:217], off offset:128
	s_waitcnt vmcnt(8) lgkmcnt(0)
	s_barrier
	s_setprio 1
	v_mfma_f32_16x16x32_bf16 v[64:67], v[68:71], v[156:159], v[64:67]
	v_mfma_f32_16x16x32_bf16 v[60:63], v[92:95], v[156:159], v[60:63]
	v_mfma_f32_16x16x32_bf16 v[48:51], v[68:71], v[172:175], v[48:51]
	v_mfma_f32_16x16x32_bf16 v[44:47], v[92:95], v[172:175], v[44:47]
	v_mfma_f32_16x16x32_bf16 v[32:35], v[68:71], v[180:183], v[32:35]
	v_mfma_f32_16x16x32_bf16 v[28:31], v[92:95], v[180:183], v[28:31]
	v_mfma_f32_16x16x32_bf16 v[16:19], v[68:71], v[188:191], v[16:19]
	v_mfma_f32_16x16x32_bf16 v[12:15], v[92:95], v[188:191], v[12:15]
	v_mfma_f32_16x16x32_bf16 v[64:67], v[80:83], v[168:171], v[64:67]
	v_mfma_f32_16x16x32_bf16 v[60:63], v[100:103], v[168:171], v[60:63]
	v_mfma_f32_16x16x32_bf16 v[48:51], v[80:83], v[176:179], v[48:51]
	v_mfma_f32_16x16x32_bf16 v[44:47], v[100:103], v[176:179], v[44:47]
	v_mfma_f32_16x16x32_bf16 v[32:35], v[80:83], v[184:187], v[32:35]
	v_mfma_f32_16x16x32_bf16 v[28:31], v[100:103], v[184:187], v[28:31]
	v_mfma_f32_16x16x32_bf16 v[16:19], v[80:83], v[208:211], v[16:19]
	v_mfma_f32_16x16x32_bf16 v[12:15], v[100:103], v[208:211], v[12:15]
	s_setprio 0
	s_setprio 1
	v_mfma_f32_16x16x32_bf16 v[56:59], v[112:115], v[156:159], v[56:59]
	v_mfma_f32_16x16x32_bf16 v[52:55], v[132:135], v[156:159], v[52:55]
	v_mfma_f32_16x16x32_bf16 v[40:43], v[112:115], v[172:175], v[40:43]
	v_mfma_f32_16x16x32_bf16 v[36:39], v[132:135], v[172:175], v[36:39]
	v_mfma_f32_16x16x32_bf16 v[24:27], v[112:115], v[180:183], v[24:27]
	v_mfma_f32_16x16x32_bf16 v[20:23], v[132:135], v[180:183], v[20:23]
	v_mfma_f32_16x16x32_bf16 v[8:11], v[112:115], v[188:191], v[8:11]
	v_mfma_f32_16x16x32_bf16 v[4:7], v[132:135], v[188:191], v[4:7]
	v_mfma_f32_16x16x32_bf16 v[56:59], v[120:123], v[168:171], v[56:59]
	v_mfma_f32_16x16x32_bf16 v[52:55], v[144:147], v[168:171], v[52:55]
	v_mfma_f32_16x16x32_bf16 v[40:43], v[120:123], v[176:179], v[40:43]
	v_mfma_f32_16x16x32_bf16 v[36:39], v[144:147], v[176:179], v[36:39]
	v_mfma_f32_16x16x32_bf16 v[24:27], v[120:123], v[184:187], v[24:27]
	v_mfma_f32_16x16x32_bf16 v[20:23], v[144:147], v[184:187], v[20:23]
	v_mfma_f32_16x16x32_bf16 v[8:11], v[120:123], v[208:211], v[8:11]
	v_mfma_f32_16x16x32_bf16 v[4:7], v[144:147], v[208:211], v[4:7]
	s_setprio 0
	s_barrier
	s_add_i32 s53, s53, 2
	s_cmp_gt_u32 s53, 41
	s_cbranch_scc0 .LBB0_480
	s_and_b64 vcc, exec, s[20:21]
	s_cbranch_vccz .LBB0_483
	s_barrier
